# sc1 write-through on the input projection's z stores (151 MB per layer, consumed from the memory-side cache by the next phases)
# baseline (speedup 1.0000x reference)
; __device__ __forceinline__ float dot4(f32x4 a) { return (a[0] * a[0] + a[1] * a[1]) + (a[2] * a[2] + a[3] * a[3]); }
; __device__ __forceinline__ float fq_sum(float s) { s += __shfl_xor(s, 16); s += __shfl_xor(s, 32); return s; }
; __device__ __forceinline__ u32x4 pack8(f32x4 a, f32x4 b) { u32x4 w; w.x = cvt_pk_bf16(a[0], a[1]); w.y = cvt_pk_bf16(a[2], a[3]); w.z = cvt_pk_bf16(b[0], b[1]); w.w = cvt_pk_bf16(b[2], b[3]); return w; }
;     __device__ __forceinline__ void operator()(const f32x4 (&acc)[2][2][4][2], const Unit& u, int wr, int wc, int fr, int fq) const {
;     ...
;                 for (int bj = 0; bj < 2; ++bj) {
;                     const f32x4 v0 = acc[ai][bj][m][0] * rs, v1 = acc[ai][bj][m][1] * rs;
;                     const int hb = 2 * u.pn + bj;
;                     if (hb < 5) { const float s = fq_sum(dot4(v0) + dot4(v1)); if (fq == 0) zs[(size_t)row * 32 + (hb < 3 ? hb * 4 : 16 + (hb - 3) * 4) + wc] = s; }
;                     if (hb == 5 && wc == 0) {
;                         const float ss = fq_sum(dot4(v0) + dot4(v1)); const float rn = rsqrtf(ss * (1.0f / 32.0f) + EPS);
;                         const f32x4 g1 = *(const f32x4*)(gk + 4 * fq), g2 = *(const f32x4*)(gk + 16 + 4 * fq);
;                         const f32x4 c = *(const f32x4*)(cs + (size_t)row * 16 + 4 * fq), s = *(const f32x4*)(sn + (size_t)row * 16 + 4 * fq);
;                         const f32x4 a = v0 * rn * g1, b = v1 * rn * g2;
;                         *(u32x4*)(kpe + (size_t)row * 32 + 8 * fq) = pack8(a * c - b * s, b * c + a * s);
;                     }
;                     *(u32x4*)(z + (size_t)row * INP + colb + bj * 128) = pack8(v0, v1);
.LBB0_365:
	s_waitcnt lgkmcnt(0)
	v_cvt_pk_bf16_f32 v142, v126, v127
	v_cvt_pk_bf16_f32 v143, v134, v135
	v_mov_b64_e32 v[134:135], s[46:47]
	v_mad_i64_i32 v[134:135], s[70:71], v206, s77, v[134:135]
	v_lshl_add_u64 v[134:135], v[176:177], 1, v[134:135]
	v_cvt_pk_bf16_f32 v144, v118, v119
	v_cvt_pk_bf16_f32 v145, v136, v137
	global_store_dwordx4 v[134:135], v[142:145], off sc1
	s_or_b32 s48, s61, 1
	s_cmp_gt_i32 s48, 4
	v_mov_b32_e32 v142, v212
	v_mov_b32_e32 v143, v212
	v_pk_mul_f32 v[136:137], v[124:125], v[142:143]
	v_pk_mul_f32 v[144:145], v[122:123], v[212:213]
	v_pk_mul_f32 v[142:143], v[116:117], v[142:143]
	v_pk_mul_f32 v[214:215], v[114:115], v[212:213]
	s_cbranch_scc1 .LBB0_369
	v_mul_f32_e32 v0, v145, v145
	v_mul_f32_e32 v207, v137, v137
	v_fmac_f32_e32 v0, v144, v144
	v_fmac_f32_e32 v207, v136, v136
	v_add_f32_e32 v0, v0, v207
	v_mul_f32_e32 v207, v215, v215
	v_mul_f32_e32 v211, v143, v143
	v_fmac_f32_e32 v207, v214, v214
	v_fmac_f32_e32 v211, v142, v142
	v_add_f32_e32 v207, v207, v211
	v_add_f32_e32 v0, v0, v207
	ds_bpermute_b32 v207, v232, v0
	s_waitcnt lgkmcnt(0)
	v_add_f32_e32 v0, v0, v207
	ds_bpermute_b32 v207, v233, v0
	s_and_saveexec_b64 s[70:71], s[38:39]
	s_cbranch_execz .LBB0_368
	s_lshl_b32 s4, s48, 2
	s_add_i32 s5, s4, 4
	s_cmp_lt_i32 s48, 3
	s_cselect_b32 s72, s4, s5
	s_ashr_i32 s73, s72, 31
	v_lshl_add_u64 v[216:217], s[50:51], 0, v[216:217]
	v_lshl_add_u64 v[216:217], s[72:73], 2, v[216:217]
	s_lshl_b32 s48, s90, 2
	s_waitcnt lgkmcnt(0)
	v_add_f32_e32 v0, v0, v207
	v_lshl_add_u64 v[216:217], v[216:217], 0, s[48:49]
	global_store_dword v[216:217], v0, off

; __device__ __forceinline__ float dot4(f32x4 a) { return (a[0] * a[0] + a[1] * a[1]) + (a[2] * a[2] + a[3] * a[3]); }
; __device__ __forceinline__ float fq_sum(float s) { s += __shfl_xor(s, 16); s += __shfl_xor(s, 32); return s; }
; __device__ __forceinline__ u32x4 pack8(f32x4 a, f32x4 b) { u32x4 w; w.x = cvt_pk_bf16(a[0], a[1]); w.y = cvt_pk_bf16(a[2], a[3]); w.z = cvt_pk_bf16(b[0], b[1]); w.w = cvt_pk_bf16(b[2], b[3]); return w; }
;     __device__ __forceinline__ void operator()(const f32x4 (&acc)[2][2][4][2], const Unit& u, int wr, int wc, int fr, int fq) const {
;     ...
;                 if (u.pn >= 5) {
;                     const f32x4 u0 = (acc[ai][0][m][0] * rs) * (acc[ai][1][m][0] * rs), u1 = (acc[ai][0][m][1] * rs) * (acc[ai][1][m][1] * rs);
;                     *(u32x4*)(z + (size_t)row * INP + 1280 + (u.pn - 5) * 128 + wc * 32 + 8 * fq) = pack8(u0, u1);
;                 } else
; #pragma unroll
;                 for (int bj = 0; bj < 2; ++bj) {
;                     const f32x4 v0 = acc[ai][bj][m][0] * rs, v1 = acc[ai][bj][m][1] * rs;
;                     const int hb = 2 * u.pn + bj;
;                     if (hb < 5) { const float s = fq_sum(dot4(v0) + dot4(v1)); if (fq == 0) zs[(size_t)row * 32 + (hb < 3 ? hb * 4 : 16 + (hb - 3) * 4) + wc] = s; }
;                     if (hb == 5 && wc == 0) {
;                         const float ss = fq_sum(dot4(v0) + dot4(v1)); const float rn = rsqrtf(ss * (1.0f / 32.0f) + EPS);
;                         const f32x4 g1 = *(const f32x4*)(gk + 4 * fq), g2 = *(const f32x4*)(gk + 16 + 4 * fq);
;                         const f32x4 c = *(const f32x4*)(cs + (size_t)row * 16 + 4 * fq), s = *(const f32x4*)(sn + (size_t)row * 16 + 4 * fq);
;                         const f32x4 a = v0 * rn * g1, b = v1 * rn * g2;
;                         *(u32x4*)(kpe + (size_t)row * 32 + 8 * fq) = pack8(a * c - b * s, b * c + a * s);
;                     }
;                     *(u32x4*)(z + (size_t)row * INP + colb + bj * 128) = pack8(v0, v1);
.LBB0_372:
.LBB0_373:
	v_mov_b32_e32 v234, v145
	v_mov_b32_e32 v235, v215
	v_mov_b32_e32 v216, v144
	v_mov_b32_e32 v217, v214
	v_pk_mul_f32 v[234:235], v[234:235], v[234:235]
	v_mov_b32_e32 v236, v137
	v_mov_b32_e32 v237, v143
	v_pk_fma_f32 v[216:217], v[216:217], v[216:217], v[234:235]
	v_mov_b32_e32 v234, v136
	v_mov_b32_e32 v235, v142
	v_pk_mul_f32 v[236:237], v[236:237], v[236:237]
	s_nop 0
	v_pk_fma_f32 v[234:235], v[234:235], v[234:235], v[236:237]
	s_nop 0
	v_pk_add_f32 v[216:217], v[216:217], v[234:235]
	global_load_dwordx4 v[234:237], v[166:167], off
	global_load_dwordx4 v[238:241], v[166:167], off offset:64
	v_add_f32_e32 v0, v216, v217
	v_lshl_add_u64 v[216:217], v[156:157], 0, v[208:209]
	global_load_dwordx4 v[242:245], v[216:217], off
	v_lshl_add_u64 v[216:217], v[158:159], 0, v[208:209]
	global_load_dwordx4 v[246:249], v[216:217], off
	s_waitcnt lgkmcnt(0)
	ds_bpermute_b32 v207, v232, v0
	v_lshl_add_u64 v[208:209], v[160:161], 0, v[208:209]
	s_waitcnt lgkmcnt(0)
	v_add_f32_e32 v0, v0, v207
	ds_bpermute_b32 v207, v233, v0
	s_waitcnt lgkmcnt(0)
	v_add_f32_e32 v0, v0, v207
	v_fmamk_f32 v0, v0, 0x3d000000, v162
	v_cmp_gt_f32_e32 vcc, s31, v0
	v_mul_f32_e32 v207, 0x4b800000, v0
	s_nop 0
	v_cndmask_b32_e32 v0, v0, v207, vcc
	v_rsq_f32_e32 v0, v0
	s_nop 0
	v_mul_f32_e32 v207, 0x45800000, v0
	v_cndmask_b32_e32 v0, v0, v207, vcc
	v_pk_mul_f32 v[216:217], v[136:137], v[0:1] op_sel_hi:[1,0]
	v_pk_mul_f32 v[250:251], v[144:145], v[0:1] op_sel_hi:[1,0]
	s_waitcnt vmcnt(3)
	v_pk_mul_f32 v[216:217], v[236:237], v[216:217]
	v_pk_mul_f32 v[236:237], v[214:215], v[0:1] op_sel_hi:[1,0]
	v_pk_mul_f32 v[234:235], v[234:235], v[250:251]
	v_pk_mul_f32 v[250:251], v[142:143], v[0:1] op_sel_hi:[1,0]
	s_waitcnt vmcnt(2)
	v_pk_mul_f32 v[236:237], v[238:239], v[236:237]
	v_pk_mul_f32 v[240:241], v[240:241], v[250:251]
	s_waitcnt vmcnt(0)
	v_pk_mul_f32 v[238:239], v[246:247], v[236:237]
	v_pk_mul_f32 v[250:251], v[248:249], v[240:241]
	v_pk_fma_f32 v[238:239], v[242:243], v[234:235], v[238:239] neg_lo:[0,0,1] neg_hi:[0,0,1]
	v_pk_mul_f32 v[234:235], v[246:247], v[234:235]
	v_pk_fma_f32 v[250:251], v[244:245], v[216:217], v[250:251] neg_lo:[0,0,1] neg_hi:[0,0,1]
	v_pk_mul_f32 v[216:217], v[248:249], v[216:217]
	v_pk_fma_f32 v[236:237], v[242:243], v[236:237], v[234:235]
	v_pk_fma_f32 v[216:217], v[244:245], v[240:241], v[216:217]
	v_cvt_pk_bf16_f32 v234, v238, v239
	v_cvt_pk_bf16_f32 v235, v250, v251
	v_cvt_pk_bf16_f32 v236, v236, v237
	s_nop 0
	v_cvt_pk_bf16_f32 v237, v216, v217
	global_store_dwordx4 v[208:209], v[234:237], off sc1
.LBB0_374:
	s_nop 1
	v_cvt_pk_bf16_f32 v234, v144, v145
	v_cvt_pk_bf16_f32 v235, v136, v137
	v_cvt_pk_bf16_f32 v236, v214, v215
	v_cvt_pk_bf16_f32 v237, v142, v143
	global_store_dwordx4 v[134:135], v[234:237], off offset:256 sc1
	s_mov_b64 s[78:79], 0
.LBB0_375:
	s_lshl_b32 s4, s68, 7
	s_add_i32 s70, s4, 0xfffffd80
	s_ashr_i32 s71, s70, 31
	s_and_b64 vcc, exec, s[78:79]
	v_lshlrev_b32_e32 v0, 1, v154
	s_cbranch_vccz .LBB0_377
	v_mov_b32_e32 v134, v212
	v_mov_b32_e32 v135, v212
	v_pk_mul_f32 v[120:121], v[120:121], v[134:135]
	v_pk_mul_f32 v[116:117], v[116:117], v[134:135]
	v_pk_mul_f32 v[114:115], v[114:115], v[212:213]
	v_pk_mul_f32 v[120:121], v[120:121], v[116:117]
	v_pk_mul_f32 v[116:117], v[118:119], v[114:115]
	v_mov_b64_e32 v[118:119], s[46:47]
	v_mad_i64_i32 v[118:119], s[72:73], v206, s77, v[118:119]
	v_lshl_add_u64 v[118:119], s[70:71], 1, v[118:119]
	s_lshl_b32 s48, s91, 1
	v_lshl_add_u64 v[118:119], v[118:119], 0, s[48:49]
	v_pk_mul_f32 v[128:129], v[128:129], v[134:135]
	v_pk_mul_f32 v[124:125], v[124:125], v[134:135]
	v_pk_mul_f32 v[122:123], v[122:123], v[212:213]
	v_lshl_add_u64 v[118:119], v[118:119], 0, v[0:1]
	v_pk_mul_f32 v[124:125], v[128:129], v[124:125]
	v_pk_mul_f32 v[122:123], v[126:127], v[122:123]
	s_nop 0
	v_cvt_pk_bf16_f32 v114, v122, v123
	v_cvt_pk_bf16_f32 v115, v124, v125
	v_cvt_pk_bf16_f32 v116, v116, v117
	v_cvt_pk_bf16_f32 v117, v120, v121
	global_store_dwordx4 v[118:119], v[114:117], off offset:2560 sc1

; __device__ __forceinline__ float dot4(f32x4 a) { return (a[0] * a[0] + a[1] * a[1]) + (a[2] * a[2] + a[3] * a[3]); }
; __device__ __forceinline__ float fq_sum(float s) { s += __shfl_xor(s, 16); s += __shfl_xor(s, 32); return s; }
; __device__ __forceinline__ u32x4 pack8(f32x4 a, f32x4 b) { u32x4 w; w.x = cvt_pk_bf16(a[0], a[1]); w.y = cvt_pk_bf16(a[2], a[3]); w.z = cvt_pk_bf16(b[0], b[1]); w.w = cvt_pk_bf16(b[2], b[3]); return w; }
;     __device__ __forceinline__ void operator()(const f32x4 (&acc)[2][2][4][2], const Unit& u, int wr, int wc, int fr, int fq) const {
;     ...
;                 for (int bj = 0; bj < 2; ++bj) {
;                     const f32x4 v0 = acc[ai][bj][m][0] * rs, v1 = acc[ai][bj][m][1] * rs;
;                     const int hb = 2 * u.pn + bj;
;                     if (hb < 5) { const float s = fq_sum(dot4(v0) + dot4(v1)); if (fq == 0) zs[(size_t)row * 32 + (hb < 3 ? hb * 4 : 16 + (hb - 3) * 4) + wc] = s; }
;                     if (hb == 5 && wc == 0) {
;                         const float ss = fq_sum(dot4(v0) + dot4(v1)); const float rn = rsqrtf(ss * (1.0f / 32.0f) + EPS);
;                         const f32x4 g1 = *(const f32x4*)(gk + 4 * fq), g2 = *(const f32x4*)(gk + 16 + 4 * fq);
;                         const f32x4 c = *(const f32x4*)(cs + (size_t)row * 16 + 4 * fq), s = *(const f32x4*)(sn + (size_t)row * 16 + 4 * fq);
;                         const f32x4 a = v0 * rn * g1, b = v1 * rn * g2;
;                         *(u32x4*)(kpe + (size_t)row * 32 + 8 * fq) = pack8(a * c - b * s, b * c + a * s);
;                     }
;                     *(u32x4*)(z + (size_t)row * INP + colb + bj * 128) = pack8(v0, v1);
.LBB0_384:
	v_cvt_pk_bf16_f32 v120, v110, v111
	s_waitcnt lgkmcnt(0)
	v_cvt_pk_bf16_f32 v121, v116, v117
	v_mov_b64_e32 v[116:117], s[46:47]
	v_mad_i64_i32 v[116:117], s[44:45], v198, s77, v[116:117]
	v_lshl_add_u64 v[116:117], v[176:177], 1, v[116:117]
	v_cvt_pk_bf16_f32 v122, v102, v103
	v_cvt_pk_bf16_f32 v123, v118, v119
	global_store_dwordx4 v[116:117], v[120:123], off sc1
	s_or_b32 s48, s61, 1
	s_cmp_gt_i32 s48, 4
	v_mov_b32_e32 v120, v114
	v_mov_b32_e32 v121, v114
	v_pk_mul_f32 v[118:119], v[108:109], v[120:121]
	v_pk_mul_f32 v[122:123], v[106:107], v[114:115]
	v_pk_mul_f32 v[120:121], v[100:101], v[120:121]
	v_pk_mul_f32 v[124:125], v[98:99], v[114:115]
	s_cbranch_scc1 .LBB0_388
	v_mul_f32_e32 v128, v123, v123
	v_mul_f32_e32 v129, v119, v119
	v_fmac_f32_e32 v128, v122, v122
	v_fmac_f32_e32 v129, v118, v118
	v_add_f32_e32 v128, v128, v129
	v_mul_f32_e32 v129, v125, v125
	v_mul_f32_e32 v134, v121, v121
	v_fmac_f32_e32 v129, v124, v124
	v_fmac_f32_e32 v134, v120, v120
	v_add_f32_e32 v129, v129, v134
	v_add_f32_e32 v128, v128, v129
	ds_bpermute_b32 v129, v232, v128
	s_waitcnt lgkmcnt(0)
	v_add_f32_e32 v128, v128, v129
	ds_bpermute_b32 v129, v233, v128
	s_and_saveexec_b64 s[44:45], s[38:39]
	s_cbranch_execz .LBB0_387
	s_lshl_b32 s4, s48, 2
	s_add_i32 s5, s4, 4
	s_cmp_lt_i32 s48, 3
	s_cselect_b32 s72, s4, s5
	s_ashr_i32 s73, s72, 31
	v_lshl_add_u64 v[126:127], s[50:51], 0, v[126:127]
	v_lshl_add_u64 v[126:127], s[72:73], 2, v[126:127]
	s_lshl_b32 s48, s90, 2
	s_waitcnt lgkmcnt(0)
	v_add_f32_e32 v128, v128, v129
	v_lshl_add_u64 v[126:127], v[126:127], 0, s[48:49]
	global_store_dword v[126:127], v128, off

; __device__ __forceinline__ float dot4(f32x4 a) { return (a[0] * a[0] + a[1] * a[1]) + (a[2] * a[2] + a[3] * a[3]); }
; __device__ __forceinline__ float fq_sum(float s) { s += __shfl_xor(s, 16); s += __shfl_xor(s, 32); return s; }
; __device__ __forceinline__ u32x4 pack8(f32x4 a, f32x4 b) { u32x4 w; w.x = cvt_pk_bf16(a[0], a[1]); w.y = cvt_pk_bf16(a[2], a[3]); w.z = cvt_pk_bf16(b[0], b[1]); w.w = cvt_pk_bf16(b[2], b[3]); return w; }
;     __device__ __forceinline__ void operator()(const f32x4 (&acc)[2][2][4][2], const Unit& u, int wr, int wc, int fr, int fq) const {
;     ...
;                 if (u.pn >= 5) {
;                     const f32x4 u0 = (acc[ai][0][m][0] * rs) * (acc[ai][1][m][0] * rs), u1 = (acc[ai][0][m][1] * rs) * (acc[ai][1][m][1] * rs);
;                     *(u32x4*)(z + (size_t)row * INP + 1280 + (u.pn - 5) * 128 + wc * 32 + 8 * fq) = pack8(u0, u1);
;                 } else
; #pragma unroll
;                 for (int bj = 0; bj < 2; ++bj) {
;                     const f32x4 v0 = acc[ai][bj][m][0] * rs, v1 = acc[ai][bj][m][1] * rs;
;                     const int hb = 2 * u.pn + bj;
;                     if (hb < 5) { const float s = fq_sum(dot4(v0) + dot4(v1)); if (fq == 0) zs[(size_t)row * 32 + (hb < 3 ? hb * 4 : 16 + (hb - 3) * 4) + wc] = s; }
;                     if (hb == 5 && wc == 0) {
;                         const float ss = fq_sum(dot4(v0) + dot4(v1)); const float rn = rsqrtf(ss * (1.0f / 32.0f) + EPS);
;                         const f32x4 g1 = *(const f32x4*)(gk + 4 * fq), g2 = *(const f32x4*)(gk + 16 + 4 * fq);
;                         const f32x4 c = *(const f32x4*)(cs + (size_t)row * 16 + 4 * fq), s = *(const f32x4*)(sn + (size_t)row * 16 + 4 * fq);
;                         const f32x4 a = v0 * rn * g1, b = v1 * rn * g2;
;                         *(u32x4*)(kpe + (size_t)row * 32 + 8 * fq) = pack8(a * c - b * s, b * c + a * s);
;                     }
;                     *(u32x4*)(z + (size_t)row * INP + colb + bj * 128) = pack8(v0, v1);
.LBB0_390:
.LBB0_391:
	v_mov_b32_e32 v128, v123
	s_waitcnt lgkmcnt(0)
	v_mov_b32_e32 v129, v125
	v_mov_b32_e32 v126, v122
	v_mov_b32_e32 v127, v124
	v_pk_mul_f32 v[128:129], v[128:129], v[128:129]
	v_mov_b32_e32 v134, v119
	v_mov_b32_e32 v135, v121
	v_pk_fma_f32 v[126:127], v[126:127], v[126:127], v[128:129]
	v_mov_b32_e32 v128, v118
	v_mov_b32_e32 v129, v120
	v_pk_mul_f32 v[134:135], v[134:135], v[134:135]
	v_lshl_add_u64 v[142:143], v[156:157], 0, v[200:201]
	v_pk_fma_f32 v[128:129], v[128:129], v[128:129], v[134:135]
	v_lshl_add_u64 v[206:207], v[158:159], 0, v[200:201]
	v_pk_add_f32 v[126:127], v[126:127], v[128:129]
	s_nop 0
	v_add_f32_e32 v126, v126, v127
	ds_bpermute_b32 v127, v232, v126
	s_waitcnt lgkmcnt(0)
	v_add_f32_e32 v126, v126, v127
	ds_bpermute_b32 v127, v233, v126
	s_waitcnt lgkmcnt(0)
	v_add_f32_e32 v126, v126, v127
	v_fmamk_f32 v126, v126, 0x3d000000, v162
	v_cmp_gt_f32_e32 vcc, s31, v126
	v_mul_f32_e32 v127, 0x4b800000, v126
	s_nop 0
	v_cndmask_b32_e32 v126, v126, v127, vcc
	v_rsq_f32_e32 v126, v126
	s_nop 0
	v_mul_f32_e32 v127, 0x45800000, v126
	v_cndmask_b32_e32 v210, v126, v127, vcc
	global_load_dwordx4 v[126:129], v[166:167], off
	global_load_dwordx4 v[134:137], v[166:167], off offset:64
	v_pk_mul_f32 v[212:213], v[118:119], v[210:211] op_sel_hi:[1,0]
	global_load_dwordx4 v[142:145], v[142:143], off
	v_pk_mul_f32 v[214:215], v[122:123], v[210:211] op_sel_hi:[1,0]
	global_load_dwordx4 v[206:209], v[206:207], off
	s_waitcnt vmcnt(3)
	v_pk_mul_f32 v[128:129], v[128:129], v[212:213]
	v_pk_mul_f32 v[212:213], v[124:125], v[210:211] op_sel_hi:[1,0]
	v_pk_mul_f32 v[210:211], v[120:121], v[210:211] op_sel_hi:[1,0]
	s_waitcnt vmcnt(2)
	v_pk_mul_f32 v[134:135], v[134:135], v[212:213]
	v_pk_mul_f32 v[136:137], v[136:137], v[210:211]
	v_pk_mul_f32 v[126:127], v[126:127], v[214:215]
	s_waitcnt vmcnt(0)
	v_pk_mul_f32 v[210:211], v[206:207], v[134:135]
	v_pk_mul_f32 v[212:213], v[208:209], v[136:137]
	v_pk_fma_f32 v[210:211], v[142:143], v[126:127], v[210:211] neg_lo:[0,0,1] neg_hi:[0,0,1]
	v_pk_fma_f32 v[212:213], v[144:145], v[128:129], v[212:213] neg_lo:[0,0,1] neg_hi:[0,0,1]
	v_pk_mul_f32 v[126:127], v[206:207], v[126:127]
	v_pk_mul_f32 v[128:129], v[208:209], v[128:129]
	s_nop 0
	v_pk_fma_f32 v[136:137], v[144:145], v[136:137], v[128:129]
	v_pk_fma_f32 v[128:129], v[142:143], v[134:135], v[126:127]
	v_lshl_add_u64 v[134:135], v[160:161], 0, v[200:201]
	v_cvt_pk_bf16_f32 v126, v210, v211
	v_cvt_pk_bf16_f32 v127, v212, v213
	v_cvt_pk_bf16_f32 v128, v128, v129
	v_cvt_pk_bf16_f32 v129, v136, v137
	global_store_dwordx4 v[134:135], v[126:129], off sc1
.LBB0_392:
	s_mov_b64 s[78:79], 0
	v_cvt_pk_bf16_f32 v122, v122, v123
	v_cvt_pk_bf16_f32 v123, v118, v119
	v_cvt_pk_bf16_f32 v124, v124, v125
	v_cvt_pk_bf16_f32 v125, v120, v121
	global_store_dwordx4 v[116:117], v[122:125], off offset:256 sc1
.LBB0_393:
	s_and_b64 vcc, exec, s[78:79]
	s_cbranch_vccz .LBB0_395
	v_mov_b32_e32 v116, v114
	v_mov_b32_e32 v117, v114
	v_pk_mul_f32 v[104:105], v[104:105], v[116:117]
	v_pk_mul_f32 v[100:101], v[100:101], v[116:117]
	v_pk_mul_f32 v[98:99], v[98:99], v[114:115]
	v_pk_mul_f32 v[104:105], v[104:105], v[100:101]
	v_pk_mul_f32 v[100:101], v[102:103], v[98:99]
	v_mov_b64_e32 v[102:103], s[46:47]
	v_mad_i64_i32 v[102:103], s[44:45], v198, s77, v[102:103]
	v_lshl_add_u64 v[102:103], s[70:71], 1, v[102:103]
	s_lshl_b32 s48, s91, 1
	v_lshl_add_u64 v[102:103], v[102:103], 0, s[48:49]
	v_pk_mul_f32 v[112:113], v[112:113], v[116:117]
	v_pk_mul_f32 v[108:109], v[108:109], v[116:117]
	v_pk_mul_f32 v[106:107], v[106:107], v[114:115]
	v_lshl_add_u64 v[102:103], v[102:103], 0, v[0:1]
	v_pk_mul_f32 v[108:109], v[112:113], v[108:109]
	v_pk_mul_f32 v[106:107], v[110:111], v[106:107]
	s_nop 0
	v_cvt_pk_bf16_f32 v98, v106, v107
	v_cvt_pk_bf16_f32 v99, v108, v109
	v_cvt_pk_bf16_f32 v100, v100, v101
	v_cvt_pk_bf16_f32 v101, v104, v105
	global_store_dwordx4 v[102:103], v[98:101], off offset:2560 sc1

; __device__ __forceinline__ float dot4(f32x4 a) { return (a[0] * a[0] + a[1] * a[1]) + (a[2] * a[2] + a[3] * a[3]); }
; __device__ __forceinline__ float fq_sum(float s) { s += __shfl_xor(s, 16); s += __shfl_xor(s, 32); return s; }
; __device__ __forceinline__ u32x4 pack8(f32x4 a, f32x4 b) { u32x4 w; w.x = cvt_pk_bf16(a[0], a[1]); w.y = cvt_pk_bf16(a[2], a[3]); w.z = cvt_pk_bf16(b[0], b[1]); w.w = cvt_pk_bf16(b[2], b[3]); return w; }
;     __device__ __forceinline__ void operator()(const f32x4 (&acc)[2][2][4][2], const Unit& u, int wr, int wc, int fr, int fq) const {
;     ...
;                 for (int bj = 0; bj < 2; ++bj) {
;                     const f32x4 v0 = acc[ai][bj][m][0] * rs, v1 = acc[ai][bj][m][1] * rs;
;                     const int hb = 2 * u.pn + bj;
;                     if (hb < 5) { const float s = fq_sum(dot4(v0) + dot4(v1)); if (fq == 0) zs[(size_t)row * 32 + (hb < 3 ? hb * 4 : 16 + (hb - 3) * 4) + wc] = s; }
;                     if (hb == 5 && wc == 0) {
;                         const float ss = fq_sum(dot4(v0) + dot4(v1)); const float rn = rsqrtf(ss * (1.0f / 32.0f) + EPS);
;                         const f32x4 g1 = *(const f32x4*)(gk + 4 * fq), g2 = *(const f32x4*)(gk + 16 + 4 * fq);
;                         const f32x4 c = *(const f32x4*)(cs + (size_t)row * 16 + 4 * fq), s = *(const f32x4*)(sn + (size_t)row * 16 + 4 * fq);
;                         const f32x4 a = v0 * rn * g1, b = v1 * rn * g2;
;                         *(u32x4*)(kpe + (size_t)row * 32 + 8 * fq) = pack8(a * c - b * s, b * c + a * s);
;                     }
;                     *(u32x4*)(z + (size_t)row * INP + colb + bj * 128) = pack8(v0, v1);
.LBB0_402:
	s_waitcnt lgkmcnt(0)
	v_cvt_pk_bf16_f32 v106, v94, v95
	v_cvt_pk_bf16_f32 v107, v102, v103
	v_mov_b64_e32 v[102:103], s[46:47]
	v_mad_i64_i32 v[102:103], s[72:73], v194, s77, v[102:103]
	v_lshl_add_u64 v[102:103], v[176:177], 1, v[102:103]
	v_cvt_pk_bf16_f32 v108, v86, v87
	v_cvt_pk_bf16_f32 v109, v104, v105
	global_store_dwordx4 v[102:103], v[106:109], off sc1
	s_or_b32 s48, s61, 1
	s_cmp_gt_i32 s48, 4
	v_mov_b32_e32 v106, v100
	v_mov_b32_e32 v107, v100
	v_pk_mul_f32 v[104:105], v[92:93], v[106:107]
	v_pk_mul_f32 v[108:109], v[90:91], v[100:101]
	v_pk_mul_f32 v[106:107], v[84:85], v[106:107]
	v_pk_mul_f32 v[110:111], v[82:83], v[100:101]
	s_cbranch_scc1 .LBB0_406
	v_mul_f32_e32 v99, v109, v109
	v_mul_f32_e32 v114, v105, v105
	v_fmac_f32_e32 v99, v108, v108
	v_fmac_f32_e32 v114, v104, v104
	v_add_f32_e32 v99, v99, v114
	v_mul_f32_e32 v114, v111, v111
	v_mul_f32_e32 v115, v107, v107
	v_fmac_f32_e32 v114, v110, v110
	v_fmac_f32_e32 v115, v106, v106
	v_add_f32_e32 v114, v114, v115
	v_add_f32_e32 v99, v99, v114
	ds_bpermute_b32 v114, v232, v99
	s_waitcnt lgkmcnt(0)
	v_add_f32_e32 v99, v99, v114
	ds_bpermute_b32 v114, v233, v99
	s_and_saveexec_b64 s[78:79], s[38:39]
	s_cbranch_execz .LBB0_405
	s_lshl_b32 s4, s48, 2
	s_add_i32 s5, s4, 4
	s_cmp_lt_i32 s48, 3
	s_cselect_b32 s72, s4, s5
	s_ashr_i32 s73, s72, 31
	v_lshl_add_u64 v[112:113], s[50:51], 0, v[112:113]
	v_lshl_add_u64 v[112:113], s[72:73], 2, v[112:113]
	s_lshl_b32 s48, s90, 2
	s_waitcnt lgkmcnt(0)
	v_add_f32_e32 v99, v99, v114
	v_lshl_add_u64 v[112:113], v[112:113], 0, s[48:49]
	global_store_dword v[112:113], v99, off

; __device__ __forceinline__ float dot4(f32x4 a) { return (a[0] * a[0] + a[1] * a[1]) + (a[2] * a[2] + a[3] * a[3]); }
; __device__ __forceinline__ float fq_sum(float s) { s += __shfl_xor(s, 16); s += __shfl_xor(s, 32); return s; }
; __device__ __forceinline__ u32x4 pack8(f32x4 a, f32x4 b) { u32x4 w; w.x = cvt_pk_bf16(a[0], a[1]); w.y = cvt_pk_bf16(a[2], a[3]); w.z = cvt_pk_bf16(b[0], b[1]); w.w = cvt_pk_bf16(b[2], b[3]); return w; }
;     __device__ __forceinline__ void operator()(const f32x4 (&acc)[2][2][4][2], const Unit& u, int wr, int wc, int fr, int fq) const {
;     ...
;                 if (u.pn >= 5) {
;                     const f32x4 u0 = (acc[ai][0][m][0] * rs) * (acc[ai][1][m][0] * rs), u1 = (acc[ai][0][m][1] * rs) * (acc[ai][1][m][1] * rs);
;                     *(u32x4*)(z + (size_t)row * INP + 1280 + (u.pn - 5) * 128 + wc * 32 + 8 * fq) = pack8(u0, u1);
;                 } else
; #pragma unroll
;                 for (int bj = 0; bj < 2; ++bj) {
;                     const f32x4 v0 = acc[ai][bj][m][0] * rs, v1 = acc[ai][bj][m][1] * rs;
;                     const int hb = 2 * u.pn + bj;
;                     if (hb < 5) { const float s = fq_sum(dot4(v0) + dot4(v1)); if (fq == 0) zs[(size_t)row * 32 + (hb < 3 ? hb * 4 : 16 + (hb - 3) * 4) + wc] = s; }
;                     if (hb == 5 && wc == 0) {
;                         const float ss = fq_sum(dot4(v0) + dot4(v1)); const float rn = rsqrtf(ss * (1.0f / 32.0f) + EPS);
;                         const f32x4 g1 = *(const f32x4*)(gk + 4 * fq), g2 = *(const f32x4*)(gk + 16 + 4 * fq);
;                         const f32x4 c = *(const f32x4*)(cs + (size_t)row * 16 + 4 * fq), s = *(const f32x4*)(sn + (size_t)row * 16 + 4 * fq);
;                         const f32x4 a = v0 * rn * g1, b = v1 * rn * g2;
;                         *(u32x4*)(kpe + (size_t)row * 32 + 8 * fq) = pack8(a * c - b * s, b * c + a * s);
;                     }
;                     *(u32x4*)(z + (size_t)row * INP + colb + bj * 128) = pack8(v0, v1);
.LBB0_408:
.LBB0_409:
	s_waitcnt lgkmcnt(0)
	v_mov_b32_e32 v114, v109
	v_mov_b32_e32 v115, v111
	v_mov_b32_e32 v112, v108
	v_mov_b32_e32 v113, v110
	v_pk_mul_f32 v[114:115], v[114:115], v[114:115]
	v_mov_b32_e32 v116, v105
	v_mov_b32_e32 v117, v107
	v_pk_fma_f32 v[112:113], v[112:113], v[112:113], v[114:115]
	v_mov_b32_e32 v114, v104
	v_mov_b32_e32 v115, v106
	v_pk_mul_f32 v[116:117], v[116:117], v[116:117]
	v_lshl_add_u64 v[120:121], v[156:157], 0, v[196:197]
	v_pk_fma_f32 v[114:115], v[114:115], v[114:115], v[116:117]
	v_lshl_add_u64 v[124:125], v[158:159], 0, v[196:197]
	v_pk_add_f32 v[112:113], v[112:113], v[114:115]
	s_nop 0
	v_add_f32_e32 v99, v112, v113
	ds_bpermute_b32 v112, v232, v99
	s_waitcnt lgkmcnt(0)
	v_add_f32_e32 v99, v99, v112
	ds_bpermute_b32 v112, v233, v99
	s_waitcnt lgkmcnt(0)
	v_add_f32_e32 v99, v99, v112
	v_fmamk_f32 v99, v99, 0x3d000000, v162
	v_cmp_gt_f32_e32 vcc, s31, v99
	v_mul_f32_e32 v112, 0x4b800000, v99
	s_nop 0
	v_cndmask_b32_e32 v99, v99, v112, vcc
	v_rsq_f32_e32 v99, v99
	s_nop 0
	v_mul_f32_e32 v112, 0x45800000, v99
	v_cndmask_b32_e32 v128, v99, v112, vcc
	global_load_dwordx4 v[112:115], v[166:167], off
	global_load_dwordx4 v[116:119], v[166:167], off offset:64
	v_pk_mul_f32 v[134:135], v[104:105], v[128:129] op_sel_hi:[1,0]
	global_load_dwordx4 v[120:123], v[120:121], off
	v_pk_mul_f32 v[136:137], v[108:109], v[128:129] op_sel_hi:[1,0]
	global_load_dwordx4 v[124:127], v[124:125], off
	s_waitcnt vmcnt(3)
	v_pk_mul_f32 v[114:115], v[114:115], v[134:135]
	v_pk_mul_f32 v[134:135], v[110:111], v[128:129] op_sel_hi:[1,0]
	v_pk_mul_f32 v[128:129], v[106:107], v[128:129] op_sel_hi:[1,0]
	s_waitcnt vmcnt(2)
	v_pk_mul_f32 v[116:117], v[116:117], v[134:135]
	v_pk_mul_f32 v[118:119], v[118:119], v[128:129]
	v_pk_mul_f32 v[112:113], v[112:113], v[136:137]
	s_waitcnt vmcnt(0)
	v_pk_mul_f32 v[128:129], v[124:125], v[116:117]
	v_pk_mul_f32 v[134:135], v[126:127], v[118:119]
	v_pk_fma_f32 v[128:129], v[120:121], v[112:113], v[128:129] neg_lo:[0,0,1] neg_hi:[0,0,1]
	v_pk_fma_f32 v[134:135], v[122:123], v[114:115], v[134:135] neg_lo:[0,0,1] neg_hi:[0,0,1]
	v_pk_mul_f32 v[112:113], v[124:125], v[112:113]
	v_pk_mul_f32 v[114:115], v[126:127], v[114:115]
	s_nop 0
	v_pk_fma_f32 v[118:119], v[122:123], v[118:119], v[114:115]
	v_pk_fma_f32 v[114:115], v[120:121], v[116:117], v[112:113]
	v_lshl_add_u64 v[116:117], v[160:161], 0, v[196:197]
	v_cvt_pk_bf16_f32 v112, v128, v129
	v_cvt_pk_bf16_f32 v113, v134, v135
	v_cvt_pk_bf16_f32 v114, v114, v115
	v_cvt_pk_bf16_f32 v115, v118, v119
	global_store_dwordx4 v[116:117], v[112:115], off sc1
.LBB0_410:
	s_mov_b64 s[78:79], 0
	v_cvt_pk_bf16_f32 v108, v108, v109
	v_cvt_pk_bf16_f32 v109, v104, v105
	v_cvt_pk_bf16_f32 v110, v110, v111
	v_cvt_pk_bf16_f32 v111, v106, v107
	global_store_dwordx4 v[102:103], v[108:111], off offset:256 sc1
.LBB0_411:
	s_and_b64 vcc, exec, s[78:79]
	s_cbranch_vccz .LBB0_413
	v_mov_b32_e32 v102, v100
	v_mov_b32_e32 v103, v100
	v_pk_mul_f32 v[88:89], v[88:89], v[102:103]
	v_pk_mul_f32 v[84:85], v[84:85], v[102:103]
	v_pk_mul_f32 v[82:83], v[82:83], v[100:101]
	v_pk_mul_f32 v[88:89], v[88:89], v[84:85]
	v_pk_mul_f32 v[84:85], v[86:87], v[82:83]
	v_mov_b64_e32 v[86:87], s[46:47]
	v_mad_i64_i32 v[86:87], s[72:73], v194, s77, v[86:87]
	v_lshl_add_u64 v[86:87], s[70:71], 1, v[86:87]
	s_lshl_b32 s48, s91, 1
	v_lshl_add_u64 v[86:87], v[86:87], 0, s[48:49]
	v_pk_mul_f32 v[96:97], v[96:97], v[102:103]
	v_pk_mul_f32 v[92:93], v[92:93], v[102:103]
	v_pk_mul_f32 v[90:91], v[90:91], v[100:101]
	v_lshl_add_u64 v[86:87], v[86:87], 0, v[0:1]
	v_pk_mul_f32 v[92:93], v[96:97], v[92:93]
	v_pk_mul_f32 v[90:91], v[94:95], v[90:91]
	s_nop 0
	v_cvt_pk_bf16_f32 v82, v90, v91
	v_cvt_pk_bf16_f32 v83, v92, v93
	v_cvt_pk_bf16_f32 v84, v84, v85
	v_cvt_pk_bf16_f32 v85, v88, v89
	global_store_dwordx4 v[86:87], v[82:85], off offset:2560 sc1

; __device__ __forceinline__ float dot4(f32x4 a) { return (a[0] * a[0] + a[1] * a[1]) + (a[2] * a[2] + a[3] * a[3]); }
; __device__ __forceinline__ float fq_sum(float s) { s += __shfl_xor(s, 16); s += __shfl_xor(s, 32); return s; }
; __device__ __forceinline__ u32x4 pack8(f32x4 a, f32x4 b) { u32x4 w; w.x = cvt_pk_bf16(a[0], a[1]); w.y = cvt_pk_bf16(a[2], a[3]); w.z = cvt_pk_bf16(b[0], b[1]); w.w = cvt_pk_bf16(b[2], b[3]); return w; }
;     __device__ __forceinline__ void operator()(const f32x4 (&acc)[2][2][4][2], const Unit& u, int wr, int wc, int fr, int fq) const {
;     ...
;                 for (int bj = 0; bj < 2; ++bj) {
;                     const f32x4 v0 = acc[ai][bj][m][0] * rs, v1 = acc[ai][bj][m][1] * rs;
;                     const int hb = 2 * u.pn + bj;
;                     if (hb < 5) { const float s = fq_sum(dot4(v0) + dot4(v1)); if (fq == 0) zs[(size_t)row * 32 + (hb < 3 ? hb * 4 : 16 + (hb - 3) * 4) + wc] = s; }
;                     if (hb == 5 && wc == 0) {
;                         const float ss = fq_sum(dot4(v0) + dot4(v1)); const float rn = rsqrtf(ss * (1.0f / 32.0f) + EPS);
;                         const f32x4 g1 = *(const f32x4*)(gk + 4 * fq), g2 = *(const f32x4*)(gk + 16 + 4 * fq);
;                         const f32x4 c = *(const f32x4*)(cs + (size_t)row * 16 + 4 * fq), s = *(const f32x4*)(sn + (size_t)row * 16 + 4 * fq);
;                         const f32x4 a = v0 * rn * g1, b = v1 * rn * g2;
;                         *(u32x4*)(kpe + (size_t)row * 32 + 8 * fq) = pack8(a * c - b * s, b * c + a * s);
;                     }
;                     *(u32x4*)(z + (size_t)row * INP + colb + bj * 128) = pack8(v0, v1);
.LBB0_420:
	v_cvt_pk_bf16_f32 v88, v78, v79
	s_waitcnt lgkmcnt(0)
	v_cvt_pk_bf16_f32 v89, v84, v85
	v_mov_b64_e32 v[84:85], s[46:47]
	v_mad_i64_i32 v[84:85], s[44:45], v190, s77, v[84:85]
	v_lshl_add_u64 v[84:85], v[176:177], 1, v[84:85]
	v_cvt_pk_bf16_f32 v90, v70, v71
	v_cvt_pk_bf16_f32 v91, v86, v87
	global_store_dwordx4 v[84:85], v[88:91], off sc1
	s_or_b32 s48, s61, 1
	s_cmp_gt_i32 s48, 4
	v_mov_b32_e32 v88, v82
	v_mov_b32_e32 v89, v82
	v_pk_mul_f32 v[86:87], v[76:77], v[88:89]
	v_pk_mul_f32 v[90:91], v[74:75], v[82:83]
	v_pk_mul_f32 v[88:89], v[68:69], v[88:89]
	v_pk_mul_f32 v[92:93], v[66:67], v[82:83]
	s_cbranch_scc1 .LBB0_424
	v_mul_f32_e32 v96, v91, v91
	v_mul_f32_e32 v97, v87, v87
	v_fmac_f32_e32 v96, v90, v90
	v_fmac_f32_e32 v97, v86, v86
	v_add_f32_e32 v96, v96, v97
	v_mul_f32_e32 v97, v93, v93
	v_mul_f32_e32 v98, v89, v89
	v_fmac_f32_e32 v97, v92, v92
	v_fmac_f32_e32 v98, v88, v88
	v_add_f32_e32 v97, v97, v98
	v_add_f32_e32 v96, v96, v97
	ds_bpermute_b32 v97, v232, v96
	s_waitcnt lgkmcnt(0)
	v_add_f32_e32 v96, v96, v97
	ds_bpermute_b32 v97, v233, v96
	s_and_saveexec_b64 s[44:45], s[38:39]
	s_cbranch_execz .LBB0_423
	s_lshl_b32 s4, s48, 2
	s_add_i32 s5, s4, 4
	s_cmp_lt_i32 s48, 3
	s_cselect_b32 s72, s4, s5
	s_ashr_i32 s73, s72, 31
	v_lshl_add_u64 v[94:95], s[50:51], 0, v[94:95]
	v_lshl_add_u64 v[94:95], s[72:73], 2, v[94:95]
	s_lshl_b32 s48, s90, 2
	s_waitcnt lgkmcnt(0)
	v_add_f32_e32 v96, v96, v97
	v_lshl_add_u64 v[94:95], v[94:95], 0, s[48:49]
	global_store_dword v[94:95], v96, off

; __device__ __forceinline__ float dot4(f32x4 a) { return (a[0] * a[0] + a[1] * a[1]) + (a[2] * a[2] + a[3] * a[3]); }
; __device__ __forceinline__ float fq_sum(float s) { s += __shfl_xor(s, 16); s += __shfl_xor(s, 32); return s; }
; __device__ __forceinline__ u32x4 pack8(f32x4 a, f32x4 b) { u32x4 w; w.x = cvt_pk_bf16(a[0], a[1]); w.y = cvt_pk_bf16(a[2], a[3]); w.z = cvt_pk_bf16(b[0], b[1]); w.w = cvt_pk_bf16(b[2], b[3]); return w; }
;     __device__ __forceinline__ void operator()(const f32x4 (&acc)[2][2][4][2], const Unit& u, int wr, int wc, int fr, int fq) const {
;     ...
;                 if (u.pn >= 5) {
;                     const f32x4 u0 = (acc[ai][0][m][0] * rs) * (acc[ai][1][m][0] * rs), u1 = (acc[ai][0][m][1] * rs) * (acc[ai][1][m][1] * rs);
;                     *(u32x4*)(z + (size_t)row * INP + 1280 + (u.pn - 5) * 128 + wc * 32 + 8 * fq) = pack8(u0, u1);
;                 } else
; #pragma unroll
;                 for (int bj = 0; bj < 2; ++bj) {
;                     const f32x4 v0 = acc[ai][bj][m][0] * rs, v1 = acc[ai][bj][m][1] * rs;
;                     const int hb = 2 * u.pn + bj;
;                     if (hb < 5) { const float s = fq_sum(dot4(v0) + dot4(v1)); if (fq == 0) zs[(size_t)row * 32 + (hb < 3 ? hb * 4 : 16 + (hb - 3) * 4) + wc] = s; }
;                     if (hb == 5 && wc == 0) {
;                         const float ss = fq_sum(dot4(v0) + dot4(v1)); const float rn = rsqrtf(ss * (1.0f / 32.0f) + EPS);
;                         const f32x4 g1 = *(const f32x4*)(gk + 4 * fq), g2 = *(const f32x4*)(gk + 16 + 4 * fq);
;                         const f32x4 c = *(const f32x4*)(cs + (size_t)row * 16 + 4 * fq), s = *(const f32x4*)(sn + (size_t)row * 16 + 4 * fq);
;                         const f32x4 a = v0 * rn * g1, b = v1 * rn * g2;
;                         *(u32x4*)(kpe + (size_t)row * 32 + 8 * fq) = pack8(a * c - b * s, b * c + a * s);
;                     }
;                     *(u32x4*)(z + (size_t)row * INP + colb + bj * 128) = pack8(v0, v1);
.LBB0_426:
.LBB0_427:
	v_mov_b32_e32 v96, v91
	s_waitcnt lgkmcnt(0)
	v_mov_b32_e32 v97, v93
	v_mov_b32_e32 v94, v90
	v_mov_b32_e32 v95, v92
	v_pk_mul_f32 v[96:97], v[96:97], v[96:97]
	v_mov_b32_e32 v98, v87
	v_mov_b32_e32 v99, v89
	v_pk_fma_f32 v[94:95], v[94:95], v[94:95], v[96:97]
	v_mov_b32_e32 v96, v86
	v_mov_b32_e32 v97, v88
	v_pk_mul_f32 v[98:99], v[98:99], v[98:99]
	v_lshl_add_u64 v[102:103], v[156:157], 0, v[192:193]
	v_pk_fma_f32 v[96:97], v[96:97], v[96:97], v[98:99]
	v_lshl_add_u64 v[106:107], v[158:159], 0, v[192:193]
	v_pk_add_f32 v[94:95], v[94:95], v[96:97]
	s_nop 0
	v_add_f32_e32 v94, v94, v95
	ds_bpermute_b32 v95, v232, v94
	s_waitcnt lgkmcnt(0)
	v_add_f32_e32 v94, v94, v95
	ds_bpermute_b32 v95, v233, v94
	s_waitcnt lgkmcnt(0)
	v_add_f32_e32 v94, v94, v95
	v_fmamk_f32 v94, v94, 0x3d000000, v162
	v_cmp_gt_f32_e32 vcc, s31, v94
	v_mul_f32_e32 v95, 0x4b800000, v94
	s_nop 0
	v_cndmask_b32_e32 v94, v94, v95, vcc
	v_rsq_f32_e32 v94, v94
	s_nop 0
	v_mul_f32_e32 v95, 0x45800000, v94
	v_cndmask_b32_e32 v110, v94, v95, vcc
	global_load_dwordx4 v[94:97], v[166:167], off
	global_load_dwordx4 v[98:101], v[166:167], off offset:64
	v_pk_mul_f32 v[112:113], v[86:87], v[110:111] op_sel_hi:[1,0]
	global_load_dwordx4 v[102:105], v[102:103], off
	v_pk_mul_f32 v[114:115], v[90:91], v[110:111] op_sel_hi:[1,0]
	global_load_dwordx4 v[106:109], v[106:107], off
	s_waitcnt vmcnt(3)
	v_pk_mul_f32 v[96:97], v[96:97], v[112:113]
	v_pk_mul_f32 v[112:113], v[92:93], v[110:111] op_sel_hi:[1,0]
	v_pk_mul_f32 v[110:111], v[88:89], v[110:111] op_sel_hi:[1,0]
	s_waitcnt vmcnt(2)
	v_pk_mul_f32 v[98:99], v[98:99], v[112:113]
	v_pk_mul_f32 v[100:101], v[100:101], v[110:111]
	v_pk_mul_f32 v[94:95], v[94:95], v[114:115]
	s_waitcnt vmcnt(0)
	v_pk_mul_f32 v[110:111], v[106:107], v[98:99]
	v_pk_mul_f32 v[112:113], v[108:109], v[100:101]
	v_pk_fma_f32 v[110:111], v[102:103], v[94:95], v[110:111] neg_lo:[0,0,1] neg_hi:[0,0,1]
	v_pk_fma_f32 v[112:113], v[104:105], v[96:97], v[112:113] neg_lo:[0,0,1] neg_hi:[0,0,1]
	v_pk_mul_f32 v[94:95], v[106:107], v[94:95]
	v_pk_mul_f32 v[96:97], v[108:109], v[96:97]
	s_nop 0
	v_pk_fma_f32 v[100:101], v[104:105], v[100:101], v[96:97]
	v_pk_fma_f32 v[96:97], v[102:103], v[98:99], v[94:95]
	v_lshl_add_u64 v[98:99], v[160:161], 0, v[192:193]
	v_cvt_pk_bf16_f32 v94, v110, v111
	v_cvt_pk_bf16_f32 v95, v112, v113
	v_cvt_pk_bf16_f32 v96, v96, v97
	v_cvt_pk_bf16_f32 v97, v100, v101
	global_store_dwordx4 v[98:99], v[94:97], off sc1
.LBB0_428:
	s_mov_b64 s[44:45], 0
	v_cvt_pk_bf16_f32 v90, v90, v91
	v_cvt_pk_bf16_f32 v91, v86, v87
	v_cvt_pk_bf16_f32 v92, v92, v93
	v_cvt_pk_bf16_f32 v93, v88, v89
	global_store_dwordx4 v[84:85], v[90:93], off offset:256 sc1
.LBB0_429:
	s_and_b64 vcc, exec, s[44:45]
	s_cbranch_vccz .LBB0_431
	v_mov_b32_e32 v84, v82
	v_mov_b32_e32 v85, v82
	v_pk_mul_f32 v[72:73], v[72:73], v[84:85]
	v_pk_mul_f32 v[68:69], v[68:69], v[84:85]
	v_pk_mul_f32 v[66:67], v[66:67], v[82:83]
	v_pk_mul_f32 v[72:73], v[72:73], v[68:69]
	v_pk_mul_f32 v[68:69], v[70:71], v[66:67]
	v_mov_b64_e32 v[70:71], s[46:47]
	v_mad_i64_i32 v[70:71], s[44:45], v190, s77, v[70:71]
	v_lshl_add_u64 v[70:71], s[70:71], 1, v[70:71]
	s_lshl_b32 s48, s91, 1
	v_lshl_add_u64 v[70:71], v[70:71], 0, s[48:49]
	v_pk_mul_f32 v[80:81], v[80:81], v[84:85]
	v_pk_mul_f32 v[76:77], v[76:77], v[84:85]
	v_pk_mul_f32 v[74:75], v[74:75], v[82:83]
	v_lshl_add_u64 v[70:71], v[70:71], 0, v[0:1]
	v_pk_mul_f32 v[76:77], v[80:81], v[76:77]
	v_pk_mul_f32 v[74:75], v[78:79], v[74:75]
	s_nop 0
	v_cvt_pk_bf16_f32 v66, v74, v75
	v_cvt_pk_bf16_f32 v67, v76, v77
	v_cvt_pk_bf16_f32 v68, v68, v69
	v_cvt_pk_bf16_f32 v69, v72, v73
	global_store_dwordx4 v[70:71], v[66:69], off offset:2560 sc1

; __device__ __forceinline__ float dot4(f32x4 a) { return (a[0] * a[0] + a[1] * a[1]) + (a[2] * a[2] + a[3] * a[3]); }
; __device__ __forceinline__ float fq_sum(float s) { s += __shfl_xor(s, 16); s += __shfl_xor(s, 32); return s; }
; __device__ __forceinline__ u32x4 pack8(f32x4 a, f32x4 b) { u32x4 w; w.x = cvt_pk_bf16(a[0], a[1]); w.y = cvt_pk_bf16(a[2], a[3]); w.z = cvt_pk_bf16(b[0], b[1]); w.w = cvt_pk_bf16(b[2], b[3]); return w; }
;     __device__ __forceinline__ void operator()(const f32x4 (&acc)[2][2][4][2], const Unit& u, int wr, int wc, int fr, int fq) const {
;     ...
;                 for (int bj = 0; bj < 2; ++bj) {
;                     const f32x4 v0 = acc[ai][bj][m][0] * rs, v1 = acc[ai][bj][m][1] * rs;
;                     const int hb = 2 * u.pn + bj;
;                     if (hb < 5) { const float s = fq_sum(dot4(v0) + dot4(v1)); if (fq == 0) zs[(size_t)row * 32 + (hb < 3 ? hb * 4 : 16 + (hb - 3) * 4) + wc] = s; }
;                     if (hb == 5 && wc == 0) {
;                         const float ss = fq_sum(dot4(v0) + dot4(v1)); const float rn = rsqrtf(ss * (1.0f / 32.0f) + EPS);
;                         const f32x4 g1 = *(const f32x4*)(gk + 4 * fq), g2 = *(const f32x4*)(gk + 16 + 4 * fq);
;                         const f32x4 c = *(const f32x4*)(cs + (size_t)row * 16 + 4 * fq), s = *(const f32x4*)(sn + (size_t)row * 16 + 4 * fq);
;                         const f32x4 a = v0 * rn * g1, b = v1 * rn * g2;
;                         *(u32x4*)(kpe + (size_t)row * 32 + 8 * fq) = pack8(a * c - b * s, b * c + a * s);
;                     }
;                     *(u32x4*)(z + (size_t)row * INP + colb + bj * 128) = pack8(v0, v1);
.LBB0_438:
	s_waitcnt lgkmcnt(0)
	v_cvt_pk_bf16_f32 v74, v62, v63
	v_cvt_pk_bf16_f32 v75, v70, v71
	v_mov_b64_e32 v[70:71], s[46:47]
	v_mad_i64_i32 v[70:71], s[72:73], v186, s77, v[70:71]
	v_lshl_add_u64 v[70:71], v[176:177], 1, v[70:71]
	v_cvt_pk_bf16_f32 v76, v54, v55
	v_cvt_pk_bf16_f32 v77, v72, v73
	global_store_dwordx4 v[70:71], v[74:77], off sc1
	s_or_b32 s48, s61, 1
	s_cmp_gt_i32 s48, 4
	v_mov_b32_e32 v74, v68
	v_mov_b32_e32 v75, v68
	v_pk_mul_f32 v[72:73], v[60:61], v[74:75]
	v_pk_mul_f32 v[76:77], v[58:59], v[68:69]
	v_pk_mul_f32 v[74:75], v[52:53], v[74:75]
	v_pk_mul_f32 v[78:79], v[50:51], v[68:69]
	s_cbranch_scc1 .LBB0_442
	v_mul_f32_e32 v67, v77, v77
	v_mul_f32_e32 v82, v73, v73
	v_fmac_f32_e32 v67, v76, v76
	v_fmac_f32_e32 v82, v72, v72
	v_add_f32_e32 v67, v67, v82
	v_mul_f32_e32 v82, v79, v79
	v_mul_f32_e32 v83, v75, v75
	v_fmac_f32_e32 v82, v78, v78
	v_fmac_f32_e32 v83, v74, v74
	v_add_f32_e32 v82, v82, v83
	v_add_f32_e32 v67, v67, v82
	ds_bpermute_b32 v82, v232, v67
	s_waitcnt lgkmcnt(0)
	v_add_f32_e32 v67, v67, v82
	ds_bpermute_b32 v82, v233, v67
	s_and_saveexec_b64 s[78:79], s[38:39]
	s_cbranch_execz .LBB0_441
	s_lshl_b32 s4, s48, 2
	s_add_i32 s5, s4, 4
	s_cmp_lt_i32 s48, 3
	s_cselect_b32 s72, s4, s5
	s_ashr_i32 s73, s72, 31
	v_lshl_add_u64 v[80:81], s[50:51], 0, v[80:81]
	v_lshl_add_u64 v[80:81], s[72:73], 2, v[80:81]
	s_lshl_b32 s48, s90, 2
	s_waitcnt lgkmcnt(0)
	v_add_f32_e32 v67, v67, v82
	v_lshl_add_u64 v[80:81], v[80:81], 0, s[48:49]
	global_store_dword v[80:81], v67, off

; __device__ __forceinline__ float dot4(f32x4 a) { return (a[0] * a[0] + a[1] * a[1]) + (a[2] * a[2] + a[3] * a[3]); }
; __device__ __forceinline__ float fq_sum(float s) { s += __shfl_xor(s, 16); s += __shfl_xor(s, 32); return s; }
; __device__ __forceinline__ u32x4 pack8(f32x4 a, f32x4 b) { u32x4 w; w.x = cvt_pk_bf16(a[0], a[1]); w.y = cvt_pk_bf16(a[2], a[3]); w.z = cvt_pk_bf16(b[0], b[1]); w.w = cvt_pk_bf16(b[2], b[3]); return w; }
;     __device__ __forceinline__ void operator()(const f32x4 (&acc)[2][2][4][2], const Unit& u, int wr, int wc, int fr, int fq) const {
;     ...
;                 if (u.pn >= 5) {
;                     const f32x4 u0 = (acc[ai][0][m][0] * rs) * (acc[ai][1][m][0] * rs), u1 = (acc[ai][0][m][1] * rs) * (acc[ai][1][m][1] * rs);
;                     *(u32x4*)(z + (size_t)row * INP + 1280 + (u.pn - 5) * 128 + wc * 32 + 8 * fq) = pack8(u0, u1);
;                 } else
; #pragma unroll
;                 for (int bj = 0; bj < 2; ++bj) {
;                     const f32x4 v0 = acc[ai][bj][m][0] * rs, v1 = acc[ai][bj][m][1] * rs;
;                     const int hb = 2 * u.pn + bj;
;                     if (hb < 5) { const float s = fq_sum(dot4(v0) + dot4(v1)); if (fq == 0) zs[(size_t)row * 32 + (hb < 3 ? hb * 4 : 16 + (hb - 3) * 4) + wc] = s; }
;                     if (hb == 5 && wc == 0) {
;                         const float ss = fq_sum(dot4(v0) + dot4(v1)); const float rn = rsqrtf(ss * (1.0f / 32.0f) + EPS);
;                         const f32x4 g1 = *(const f32x4*)(gk + 4 * fq), g2 = *(const f32x4*)(gk + 16 + 4 * fq);
;                         const f32x4 c = *(const f32x4*)(cs + (size_t)row * 16 + 4 * fq), s = *(const f32x4*)(sn + (size_t)row * 16 + 4 * fq);
;                         const f32x4 a = v0 * rn * g1, b = v1 * rn * g2;
;                         *(u32x4*)(kpe + (size_t)row * 32 + 8 * fq) = pack8(a * c - b * s, b * c + a * s);
;                     }
;                     *(u32x4*)(z + (size_t)row * INP + colb + bj * 128) = pack8(v0, v1);
.LBB0_444:
.LBB0_445:
	s_waitcnt lgkmcnt(0)
	v_mov_b32_e32 v82, v77
	v_mov_b32_e32 v83, v79
	v_mov_b32_e32 v80, v76
	v_mov_b32_e32 v81, v78
	v_pk_mul_f32 v[82:83], v[82:83], v[82:83]
	v_mov_b32_e32 v84, v73
	v_mov_b32_e32 v85, v75
	v_pk_fma_f32 v[80:81], v[80:81], v[80:81], v[82:83]
	v_mov_b32_e32 v82, v72
	v_mov_b32_e32 v83, v74
	v_pk_mul_f32 v[84:85], v[84:85], v[84:85]
	v_lshl_add_u64 v[88:89], v[156:157], 0, v[188:189]
	v_pk_fma_f32 v[82:83], v[82:83], v[82:83], v[84:85]
	v_lshl_add_u64 v[92:93], v[158:159], 0, v[188:189]
	v_pk_add_f32 v[80:81], v[80:81], v[82:83]
	s_nop 0
	v_add_f32_e32 v67, v80, v81
	ds_bpermute_b32 v80, v232, v67
	s_waitcnt lgkmcnt(0)
	v_add_f32_e32 v67, v67, v80
	ds_bpermute_b32 v80, v233, v67
	s_waitcnt lgkmcnt(0)
	v_add_f32_e32 v67, v67, v80
	v_fmamk_f32 v67, v67, 0x3d000000, v162
	v_cmp_gt_f32_e32 vcc, s31, v67
	v_mul_f32_e32 v80, 0x4b800000, v67
	s_nop 0
	v_cndmask_b32_e32 v67, v67, v80, vcc
	v_rsq_f32_e32 v67, v67
	s_nop 0
	v_mul_f32_e32 v80, 0x45800000, v67
	v_cndmask_b32_e32 v96, v67, v80, vcc
	global_load_dwordx4 v[80:83], v[166:167], off
	global_load_dwordx4 v[84:87], v[166:167], off offset:64
	v_pk_mul_f32 v[98:99], v[72:73], v[96:97] op_sel_hi:[1,0]
	global_load_dwordx4 v[88:91], v[88:89], off
	v_pk_mul_f32 v[100:101], v[76:77], v[96:97] op_sel_hi:[1,0]
	global_load_dwordx4 v[92:95], v[92:93], off
	s_waitcnt vmcnt(3)
	v_pk_mul_f32 v[82:83], v[82:83], v[98:99]
	v_pk_mul_f32 v[98:99], v[78:79], v[96:97] op_sel_hi:[1,0]
	v_pk_mul_f32 v[96:97], v[74:75], v[96:97] op_sel_hi:[1,0]
	s_waitcnt vmcnt(2)
	v_pk_mul_f32 v[84:85], v[84:85], v[98:99]
	v_pk_mul_f32 v[86:87], v[86:87], v[96:97]
	v_pk_mul_f32 v[80:81], v[80:81], v[100:101]
	s_waitcnt vmcnt(0)
	v_pk_mul_f32 v[96:97], v[92:93], v[84:85]
	v_pk_mul_f32 v[98:99], v[94:95], v[86:87]
	v_pk_fma_f32 v[96:97], v[88:89], v[80:81], v[96:97] neg_lo:[0,0,1] neg_hi:[0,0,1]
	v_pk_fma_f32 v[98:99], v[90:91], v[82:83], v[98:99] neg_lo:[0,0,1] neg_hi:[0,0,1]
	v_pk_mul_f32 v[80:81], v[92:93], v[80:81]
	v_pk_mul_f32 v[82:83], v[94:95], v[82:83]
	s_nop 0
	v_pk_fma_f32 v[86:87], v[90:91], v[86:87], v[82:83]
	v_pk_fma_f32 v[82:83], v[88:89], v[84:85], v[80:81]
	v_lshl_add_u64 v[84:85], v[160:161], 0, v[188:189]
	v_cvt_pk_bf16_f32 v80, v96, v97
	v_cvt_pk_bf16_f32 v81, v98, v99
	v_cvt_pk_bf16_f32 v82, v82, v83
	v_cvt_pk_bf16_f32 v83, v86, v87
	global_store_dwordx4 v[84:85], v[80:83], off sc1
.LBB0_446:
	s_mov_b64 s[78:79], 0
	v_cvt_pk_bf16_f32 v76, v76, v77
	v_cvt_pk_bf16_f32 v77, v72, v73
	v_cvt_pk_bf16_f32 v78, v78, v79
	v_cvt_pk_bf16_f32 v79, v74, v75
	global_store_dwordx4 v[70:71], v[76:79], off offset:256 sc1
.LBB0_447:
	s_and_b64 vcc, exec, s[78:79]
	s_cbranch_vccz .LBB0_449
	v_mov_b32_e32 v70, v68
	v_mov_b32_e32 v71, v68
	v_pk_mul_f32 v[56:57], v[56:57], v[70:71]
	v_pk_mul_f32 v[52:53], v[52:53], v[70:71]
	v_pk_mul_f32 v[50:51], v[50:51], v[68:69]
	v_pk_mul_f32 v[56:57], v[56:57], v[52:53]
	v_pk_mul_f32 v[52:53], v[54:55], v[50:51]
	v_mov_b64_e32 v[54:55], s[46:47]
	v_mad_i64_i32 v[54:55], s[72:73], v186, s77, v[54:55]
	v_lshl_add_u64 v[54:55], s[70:71], 1, v[54:55]
	s_lshl_b32 s48, s91, 1
	v_lshl_add_u64 v[54:55], v[54:55], 0, s[48:49]
	v_pk_mul_f32 v[64:65], v[64:65], v[70:71]
	v_pk_mul_f32 v[60:61], v[60:61], v[70:71]
	v_pk_mul_f32 v[58:59], v[58:59], v[68:69]
	v_lshl_add_u64 v[54:55], v[54:55], 0, v[0:1]
	v_pk_mul_f32 v[60:61], v[64:65], v[60:61]
	v_pk_mul_f32 v[58:59], v[62:63], v[58:59]
	s_nop 0
	v_cvt_pk_bf16_f32 v50, v58, v59
	v_cvt_pk_bf16_f32 v51, v60, v61
	v_cvt_pk_bf16_f32 v52, v52, v53
	v_cvt_pk_bf16_f32 v53, v56, v57
	global_store_dwordx4 v[54:55], v[50:53], off offset:2560 sc1

; __device__ __forceinline__ float dot4(f32x4 a) { return (a[0] * a[0] + a[1] * a[1]) + (a[2] * a[2] + a[3] * a[3]); }
; __device__ __forceinline__ float fq_sum(float s) { s += __shfl_xor(s, 16); s += __shfl_xor(s, 32); return s; }
; __device__ __forceinline__ u32x4 pack8(f32x4 a, f32x4 b) { u32x4 w; w.x = cvt_pk_bf16(a[0], a[1]); w.y = cvt_pk_bf16(a[2], a[3]); w.z = cvt_pk_bf16(b[0], b[1]); w.w = cvt_pk_bf16(b[2], b[3]); return w; }
;     __device__ __forceinline__ void operator()(const f32x4 (&acc)[2][2][4][2], const Unit& u, int wr, int wc, int fr, int fq) const {
;     ...
;                 for (int bj = 0; bj < 2; ++bj) {
;                     const f32x4 v0 = acc[ai][bj][m][0] * rs, v1 = acc[ai][bj][m][1] * rs;
;                     const int hb = 2 * u.pn + bj;
;                     if (hb < 5) { const float s = fq_sum(dot4(v0) + dot4(v1)); if (fq == 0) zs[(size_t)row * 32 + (hb < 3 ? hb * 4 : 16 + (hb - 3) * 4) + wc] = s; }
;                     if (hb == 5 && wc == 0) {
;                         const float ss = fq_sum(dot4(v0) + dot4(v1)); const float rn = rsqrtf(ss * (1.0f / 32.0f) + EPS);
;                         const f32x4 g1 = *(const f32x4*)(gk + 4 * fq), g2 = *(const f32x4*)(gk + 16 + 4 * fq);
;                         const f32x4 c = *(const f32x4*)(cs + (size_t)row * 16 + 4 * fq), s = *(const f32x4*)(sn + (size_t)row * 16 + 4 * fq);
;                         const f32x4 a = v0 * rn * g1, b = v1 * rn * g2;
;                         *(u32x4*)(kpe + (size_t)row * 32 + 8 * fq) = pack8(a * c - b * s, b * c + a * s);
;                     }
;                     *(u32x4*)(z + (size_t)row * INP + colb + bj * 128) = pack8(v0, v1);
.LBB0_456:
	v_cvt_pk_bf16_f32 v56, v46, v47
	s_waitcnt lgkmcnt(0)
	v_cvt_pk_bf16_f32 v57, v52, v53
	v_mov_b64_e32 v[52:53], s[46:47]
	v_mad_i64_i32 v[52:53], s[44:45], v182, s77, v[52:53]
	v_lshl_add_u64 v[52:53], v[176:177], 1, v[52:53]
	v_cvt_pk_bf16_f32 v58, v38, v39
	v_cvt_pk_bf16_f32 v59, v54, v55
	global_store_dwordx4 v[52:53], v[56:59], off sc1
	s_or_b32 s48, s61, 1
	s_cmp_gt_i32 s48, 4
	v_mov_b32_e32 v56, v50
	v_mov_b32_e32 v57, v50
	v_pk_mul_f32 v[54:55], v[44:45], v[56:57]
	v_pk_mul_f32 v[58:59], v[42:43], v[50:51]
	v_pk_mul_f32 v[56:57], v[36:37], v[56:57]
	v_pk_mul_f32 v[60:61], v[34:35], v[50:51]
	s_cbranch_scc1 .LBB0_460
	v_mul_f32_e32 v64, v59, v59
	v_mul_f32_e32 v65, v55, v55
	v_fmac_f32_e32 v64, v58, v58
	v_fmac_f32_e32 v65, v54, v54
	v_add_f32_e32 v64, v64, v65
	v_mul_f32_e32 v65, v61, v61
	v_mul_f32_e32 v66, v57, v57
	v_fmac_f32_e32 v65, v60, v60
	v_fmac_f32_e32 v66, v56, v56
	v_add_f32_e32 v65, v65, v66
	v_add_f32_e32 v64, v64, v65
	ds_bpermute_b32 v65, v232, v64
	s_waitcnt lgkmcnt(0)
	v_add_f32_e32 v64, v64, v65
	ds_bpermute_b32 v65, v233, v64
	s_and_saveexec_b64 s[44:45], s[38:39]
	s_cbranch_execz .LBB0_459
	s_lshl_b32 s4, s48, 2
	s_add_i32 s5, s4, 4
	s_cmp_lt_i32 s48, 3
	s_cselect_b32 s72, s4, s5
	s_ashr_i32 s73, s72, 31
	v_lshl_add_u64 v[62:63], s[50:51], 0, v[62:63]
	v_lshl_add_u64 v[62:63], s[72:73], 2, v[62:63]
	s_lshl_b32 s48, s90, 2
	s_waitcnt lgkmcnt(0)
	v_add_f32_e32 v64, v64, v65
	v_lshl_add_u64 v[62:63], v[62:63], 0, s[48:49]
	global_store_dword v[62:63], v64, off

; __device__ __forceinline__ float dot4(f32x4 a) { return (a[0] * a[0] + a[1] * a[1]) + (a[2] * a[2] + a[3] * a[3]); }
; __device__ __forceinline__ float fq_sum(float s) { s += __shfl_xor(s, 16); s += __shfl_xor(s, 32); return s; }
; __device__ __forceinline__ u32x4 pack8(f32x4 a, f32x4 b) { u32x4 w; w.x = cvt_pk_bf16(a[0], a[1]); w.y = cvt_pk_bf16(a[2], a[3]); w.z = cvt_pk_bf16(b[0], b[1]); w.w = cvt_pk_bf16(b[2], b[3]); return w; }
;     __device__ __forceinline__ void operator()(const f32x4 (&acc)[2][2][4][2], const Unit& u, int wr, int wc, int fr, int fq) const {
;     ...
;                 if (u.pn >= 5) {
;                     const f32x4 u0 = (acc[ai][0][m][0] * rs) * (acc[ai][1][m][0] * rs), u1 = (acc[ai][0][m][1] * rs) * (acc[ai][1][m][1] * rs);
;                     *(u32x4*)(z + (size_t)row * INP + 1280 + (u.pn - 5) * 128 + wc * 32 + 8 * fq) = pack8(u0, u1);
;                 } else
; #pragma unroll
;                 for (int bj = 0; bj < 2; ++bj) {
;                     const f32x4 v0 = acc[ai][bj][m][0] * rs, v1 = acc[ai][bj][m][1] * rs;
;                     const int hb = 2 * u.pn + bj;
;                     if (hb < 5) { const float s = fq_sum(dot4(v0) + dot4(v1)); if (fq == 0) zs[(size_t)row * 32 + (hb < 3 ? hb * 4 : 16 + (hb - 3) * 4) + wc] = s; }
;                     if (hb == 5 && wc == 0) {
;                         const float ss = fq_sum(dot4(v0) + dot4(v1)); const float rn = rsqrtf(ss * (1.0f / 32.0f) + EPS);
;                         const f32x4 g1 = *(const f32x4*)(gk + 4 * fq), g2 = *(const f32x4*)(gk + 16 + 4 * fq);
;                         const f32x4 c = *(const f32x4*)(cs + (size_t)row * 16 + 4 * fq), s = *(const f32x4*)(sn + (size_t)row * 16 + 4 * fq);
;                         const f32x4 a = v0 * rn * g1, b = v1 * rn * g2;
;                         *(u32x4*)(kpe + (size_t)row * 32 + 8 * fq) = pack8(a * c - b * s, b * c + a * s);
;                     }
;                     *(u32x4*)(z + (size_t)row * INP + colb + bj * 128) = pack8(v0, v1);
.LBB0_462:
.LBB0_463:
	v_mov_b32_e32 v64, v59
	s_waitcnt lgkmcnt(0)
	v_mov_b32_e32 v65, v61
	v_mov_b32_e32 v62, v58
	v_mov_b32_e32 v63, v60
	v_pk_mul_f32 v[64:65], v[64:65], v[64:65]
	v_mov_b32_e32 v66, v55
	v_mov_b32_e32 v67, v57
	v_pk_fma_f32 v[62:63], v[62:63], v[62:63], v[64:65]
	v_mov_b32_e32 v64, v54
	v_mov_b32_e32 v65, v56
	v_pk_mul_f32 v[66:67], v[66:67], v[66:67]
	v_lshl_add_u64 v[70:71], v[156:157], 0, v[184:185]
	v_pk_fma_f32 v[64:65], v[64:65], v[64:65], v[66:67]
	v_lshl_add_u64 v[74:75], v[158:159], 0, v[184:185]
	v_pk_add_f32 v[62:63], v[62:63], v[64:65]
	s_nop 0
	v_add_f32_e32 v62, v62, v63
	ds_bpermute_b32 v63, v232, v62
	s_waitcnt lgkmcnt(0)
	v_add_f32_e32 v62, v62, v63
	ds_bpermute_b32 v63, v233, v62
	s_waitcnt lgkmcnt(0)
	v_add_f32_e32 v62, v62, v63
	v_fmamk_f32 v62, v62, 0x3d000000, v162
	v_cmp_gt_f32_e32 vcc, s31, v62
	v_mul_f32_e32 v63, 0x4b800000, v62
	s_nop 0
	v_cndmask_b32_e32 v62, v62, v63, vcc
	v_rsq_f32_e32 v62, v62
	s_nop 0
	v_mul_f32_e32 v63, 0x45800000, v62
	v_cndmask_b32_e32 v78, v62, v63, vcc
	global_load_dwordx4 v[62:65], v[166:167], off
	global_load_dwordx4 v[66:69], v[166:167], off offset:64
	v_pk_mul_f32 v[80:81], v[54:55], v[78:79] op_sel_hi:[1,0]
	global_load_dwordx4 v[70:73], v[70:71], off
	v_pk_mul_f32 v[82:83], v[58:59], v[78:79] op_sel_hi:[1,0]
	global_load_dwordx4 v[74:77], v[74:75], off
	s_waitcnt vmcnt(3)
	v_pk_mul_f32 v[64:65], v[64:65], v[80:81]
	v_pk_mul_f32 v[80:81], v[60:61], v[78:79] op_sel_hi:[1,0]
	v_pk_mul_f32 v[78:79], v[56:57], v[78:79] op_sel_hi:[1,0]
	s_waitcnt vmcnt(2)
	v_pk_mul_f32 v[66:67], v[66:67], v[80:81]
	v_pk_mul_f32 v[68:69], v[68:69], v[78:79]
	v_pk_mul_f32 v[62:63], v[62:63], v[82:83]
	s_waitcnt vmcnt(0)
	v_pk_mul_f32 v[78:79], v[74:75], v[66:67]
	v_pk_mul_f32 v[80:81], v[76:77], v[68:69]
	v_pk_fma_f32 v[78:79], v[70:71], v[62:63], v[78:79] neg_lo:[0,0,1] neg_hi:[0,0,1]
	v_pk_fma_f32 v[80:81], v[72:73], v[64:65], v[80:81] neg_lo:[0,0,1] neg_hi:[0,0,1]
	v_pk_mul_f32 v[62:63], v[74:75], v[62:63]
	v_pk_mul_f32 v[64:65], v[76:77], v[64:65]
	s_nop 0
	v_pk_fma_f32 v[68:69], v[72:73], v[68:69], v[64:65]
	v_pk_fma_f32 v[64:65], v[70:71], v[66:67], v[62:63]
	v_lshl_add_u64 v[66:67], v[160:161], 0, v[184:185]
	v_cvt_pk_bf16_f32 v62, v78, v79
	v_cvt_pk_bf16_f32 v63, v80, v81
	v_cvt_pk_bf16_f32 v64, v64, v65
	v_cvt_pk_bf16_f32 v65, v68, v69
	global_store_dwordx4 v[66:67], v[62:65], off sc1
.LBB0_464:
	s_mov_b64 s[44:45], 0
	v_cvt_pk_bf16_f32 v58, v58, v59
	v_cvt_pk_bf16_f32 v59, v54, v55
	v_cvt_pk_bf16_f32 v60, v60, v61
	v_cvt_pk_bf16_f32 v61, v56, v57
	global_store_dwordx4 v[52:53], v[58:61], off offset:256 sc1
.LBB0_465:
	s_and_b64 vcc, exec, s[44:45]
	s_cbranch_vccz .LBB0_467
	v_mov_b32_e32 v52, v50
	v_mov_b32_e32 v53, v50
	v_pk_mul_f32 v[40:41], v[40:41], v[52:53]
	v_pk_mul_f32 v[36:37], v[36:37], v[52:53]
	v_pk_mul_f32 v[34:35], v[34:35], v[50:51]
	v_pk_mul_f32 v[40:41], v[40:41], v[36:37]
	v_pk_mul_f32 v[36:37], v[38:39], v[34:35]
	v_mov_b64_e32 v[38:39], s[46:47]
	v_mad_i64_i32 v[38:39], s[44:45], v182, s77, v[38:39]
	v_lshl_add_u64 v[38:39], s[70:71], 1, v[38:39]
	s_lshl_b32 s48, s91, 1
	v_lshl_add_u64 v[38:39], v[38:39], 0, s[48:49]
	v_pk_mul_f32 v[48:49], v[48:49], v[52:53]
	v_pk_mul_f32 v[44:45], v[44:45], v[52:53]
	v_pk_mul_f32 v[42:43], v[42:43], v[50:51]
	v_lshl_add_u64 v[38:39], v[38:39], 0, v[0:1]
	v_pk_mul_f32 v[44:45], v[48:49], v[44:45]
	v_pk_mul_f32 v[42:43], v[46:47], v[42:43]
	s_nop 0
	v_cvt_pk_bf16_f32 v34, v42, v43
	v_cvt_pk_bf16_f32 v35, v44, v45
	v_cvt_pk_bf16_f32 v36, v36, v37
	v_cvt_pk_bf16_f32 v37, v40, v41
	global_store_dwordx4 v[38:39], v[34:37], off offset:2560 sc1

; __device__ __forceinline__ float dot4(f32x4 a) { return (a[0] * a[0] + a[1] * a[1]) + (a[2] * a[2] + a[3] * a[3]); }
; __device__ __forceinline__ float fq_sum(float s) { s += __shfl_xor(s, 16); s += __shfl_xor(s, 32); return s; }
; __device__ __forceinline__ u32x4 pack8(f32x4 a, f32x4 b) { u32x4 w; w.x = cvt_pk_bf16(a[0], a[1]); w.y = cvt_pk_bf16(a[2], a[3]); w.z = cvt_pk_bf16(b[0], b[1]); w.w = cvt_pk_bf16(b[2], b[3]); return w; }
;     __device__ __forceinline__ void operator()(const f32x4 (&acc)[2][2][4][2], const Unit& u, int wr, int wc, int fr, int fq) const {
;     ...
;                 for (int bj = 0; bj < 2; ++bj) {
;                     const f32x4 v0 = acc[ai][bj][m][0] * rs, v1 = acc[ai][bj][m][1] * rs;
;                     const int hb = 2 * u.pn + bj;
;                     if (hb < 5) { const float s = fq_sum(dot4(v0) + dot4(v1)); if (fq == 0) zs[(size_t)row * 32 + (hb < 3 ? hb * 4 : 16 + (hb - 3) * 4) + wc] = s; }
;                     if (hb == 5 && wc == 0) {
;                         const float ss = fq_sum(dot4(v0) + dot4(v1)); const float rn = rsqrtf(ss * (1.0f / 32.0f) + EPS);
;                         const f32x4 g1 = *(const f32x4*)(gk + 4 * fq), g2 = *(const f32x4*)(gk + 16 + 4 * fq);
;                         const f32x4 c = *(const f32x4*)(cs + (size_t)row * 16 + 4 * fq), s = *(const f32x4*)(sn + (size_t)row * 16 + 4 * fq);
;                         const f32x4 a = v0 * rn * g1, b = v1 * rn * g2;
;                         *(u32x4*)(kpe + (size_t)row * 32 + 8 * fq) = pack8(a * c - b * s, b * c + a * s);
;                     }
;                     *(u32x4*)(z + (size_t)row * INP + colb + bj * 128) = pack8(v0, v1);
.LBB0_474:
	s_waitcnt lgkmcnt(0)
	v_cvt_pk_bf16_f32 v42, v30, v31
	v_cvt_pk_bf16_f32 v43, v38, v39
	v_mov_b64_e32 v[38:39], s[46:47]
	v_mad_i64_i32 v[38:39], s[72:73], v178, s77, v[38:39]
	v_lshl_add_u64 v[38:39], v[176:177], 1, v[38:39]
	v_cvt_pk_bf16_f32 v44, v22, v23
	v_cvt_pk_bf16_f32 v45, v40, v41
	global_store_dwordx4 v[38:39], v[42:45], off sc1
	s_or_b32 s48, s61, 1
	s_cmp_gt_i32 s48, 4
	v_mov_b32_e32 v42, v36
	v_mov_b32_e32 v43, v36
	v_pk_mul_f32 v[40:41], v[28:29], v[42:43]
	v_pk_mul_f32 v[44:45], v[26:27], v[36:37]
	v_pk_mul_f32 v[42:43], v[20:21], v[42:43]
	v_pk_mul_f32 v[46:47], v[18:19], v[36:37]
	s_cbranch_scc1 .LBB0_478
	v_mul_f32_e32 v35, v45, v45
	v_mul_f32_e32 v50, v41, v41
	v_fmac_f32_e32 v35, v44, v44
	v_fmac_f32_e32 v50, v40, v40
	v_add_f32_e32 v35, v35, v50
	v_mul_f32_e32 v50, v47, v47
	v_mul_f32_e32 v51, v43, v43
	v_fmac_f32_e32 v50, v46, v46
	v_fmac_f32_e32 v51, v42, v42
	v_add_f32_e32 v50, v50, v51
	v_add_f32_e32 v35, v35, v50
	ds_bpermute_b32 v50, v232, v35
	s_waitcnt lgkmcnt(0)
	v_add_f32_e32 v35, v35, v50
	ds_bpermute_b32 v50, v233, v35
	s_and_saveexec_b64 s[78:79], s[38:39]
	s_cbranch_execz .LBB0_477
	s_lshl_b32 s4, s48, 2
	s_add_i32 s5, s4, 4
	s_cmp_lt_i32 s48, 3
	s_cselect_b32 s72, s4, s5
	s_ashr_i32 s73, s72, 31
	v_lshl_add_u64 v[48:49], s[50:51], 0, v[48:49]
	v_lshl_add_u64 v[48:49], s[72:73], 2, v[48:49]
	s_lshl_b32 s48, s90, 2
	s_waitcnt lgkmcnt(0)
	v_add_f32_e32 v35, v35, v50
	v_lshl_add_u64 v[48:49], v[48:49], 0, s[48:49]
	global_store_dword v[48:49], v35, off

; __device__ __forceinline__ float dot4(f32x4 a) { return (a[0] * a[0] + a[1] * a[1]) + (a[2] * a[2] + a[3] * a[3]); }
; __device__ __forceinline__ float fq_sum(float s) { s += __shfl_xor(s, 16); s += __shfl_xor(s, 32); return s; }
; __device__ __forceinline__ u32x4 pack8(f32x4 a, f32x4 b) { u32x4 w; w.x = cvt_pk_bf16(a[0], a[1]); w.y = cvt_pk_bf16(a[2], a[3]); w.z = cvt_pk_bf16(b[0], b[1]); w.w = cvt_pk_bf16(b[2], b[3]); return w; }
;     __device__ __forceinline__ void operator()(const f32x4 (&acc)[2][2][4][2], const Unit& u, int wr, int wc, int fr, int fq) const {
;     ...
;                 if (u.pn >= 5) {
;                     const f32x4 u0 = (acc[ai][0][m][0] * rs) * (acc[ai][1][m][0] * rs), u1 = (acc[ai][0][m][1] * rs) * (acc[ai][1][m][1] * rs);
;                     *(u32x4*)(z + (size_t)row * INP + 1280 + (u.pn - 5) * 128 + wc * 32 + 8 * fq) = pack8(u0, u1);
;                 } else
; #pragma unroll
;                 for (int bj = 0; bj < 2; ++bj) {
;                     const f32x4 v0 = acc[ai][bj][m][0] * rs, v1 = acc[ai][bj][m][1] * rs;
;                     const int hb = 2 * u.pn + bj;
;                     if (hb < 5) { const float s = fq_sum(dot4(v0) + dot4(v1)); if (fq == 0) zs[(size_t)row * 32 + (hb < 3 ? hb * 4 : 16 + (hb - 3) * 4) + wc] = s; }
;                     if (hb == 5 && wc == 0) {
;                         const float ss = fq_sum(dot4(v0) + dot4(v1)); const float rn = rsqrtf(ss * (1.0f / 32.0f) + EPS);
;                         const f32x4 g1 = *(const f32x4*)(gk + 4 * fq), g2 = *(const f32x4*)(gk + 16 + 4 * fq);
;                         const f32x4 c = *(const f32x4*)(cs + (size_t)row * 16 + 4 * fq), s = *(const f32x4*)(sn + (size_t)row * 16 + 4 * fq);
;                         const f32x4 a = v0 * rn * g1, b = v1 * rn * g2;
;                         *(u32x4*)(kpe + (size_t)row * 32 + 8 * fq) = pack8(a * c - b * s, b * c + a * s);
;                     }
;                     *(u32x4*)(z + (size_t)row * INP + colb + bj * 128) = pack8(v0, v1);
.LBB0_480:
.LBB0_481:
	s_waitcnt lgkmcnt(0)
	v_mov_b32_e32 v50, v45
	v_mov_b32_e32 v51, v47
	v_mov_b32_e32 v48, v44
	v_mov_b32_e32 v49, v46
	v_pk_mul_f32 v[50:51], v[50:51], v[50:51]
	v_mov_b32_e32 v52, v41
	v_mov_b32_e32 v53, v43
	v_pk_fma_f32 v[48:49], v[48:49], v[48:49], v[50:51]
	v_mov_b32_e32 v50, v40
	v_mov_b32_e32 v51, v42
	v_pk_mul_f32 v[52:53], v[52:53], v[52:53]
	v_lshl_add_u64 v[56:57], v[156:157], 0, v[180:181]
	v_pk_fma_f32 v[50:51], v[50:51], v[50:51], v[52:53]
	v_lshl_add_u64 v[60:61], v[158:159], 0, v[180:181]
	v_pk_add_f32 v[48:49], v[48:49], v[50:51]
	s_nop 0
	v_add_f32_e32 v35, v48, v49
	ds_bpermute_b32 v48, v232, v35
	s_waitcnt lgkmcnt(0)
	v_add_f32_e32 v35, v35, v48
	ds_bpermute_b32 v48, v233, v35
	s_waitcnt lgkmcnt(0)
	v_add_f32_e32 v35, v35, v48
	v_fmamk_f32 v35, v35, 0x3d000000, v162
	v_cmp_gt_f32_e32 vcc, s31, v35
	v_mul_f32_e32 v48, 0x4b800000, v35
	s_nop 0
	v_cndmask_b32_e32 v35, v35, v48, vcc
	v_rsq_f32_e32 v35, v35
	s_nop 0
	v_mul_f32_e32 v48, 0x45800000, v35
	v_cndmask_b32_e32 v64, v35, v48, vcc
	global_load_dwordx4 v[48:51], v[166:167], off
	global_load_dwordx4 v[52:55], v[166:167], off offset:64
	v_pk_mul_f32 v[66:67], v[40:41], v[64:65] op_sel_hi:[1,0]
	global_load_dwordx4 v[56:59], v[56:57], off
	v_pk_mul_f32 v[68:69], v[44:45], v[64:65] op_sel_hi:[1,0]
	global_load_dwordx4 v[60:63], v[60:61], off
	s_waitcnt vmcnt(3)
	v_pk_mul_f32 v[50:51], v[50:51], v[66:67]
	v_pk_mul_f32 v[66:67], v[46:47], v[64:65] op_sel_hi:[1,0]
	v_pk_mul_f32 v[64:65], v[42:43], v[64:65] op_sel_hi:[1,0]
	s_waitcnt vmcnt(2)
	v_pk_mul_f32 v[52:53], v[52:53], v[66:67]
	v_pk_mul_f32 v[54:55], v[54:55], v[64:65]
	v_pk_mul_f32 v[48:49], v[48:49], v[68:69]
	s_waitcnt vmcnt(0)
	v_pk_mul_f32 v[64:65], v[60:61], v[52:53]
	v_pk_mul_f32 v[66:67], v[62:63], v[54:55]
	v_pk_fma_f32 v[64:65], v[56:57], v[48:49], v[64:65] neg_lo:[0,0,1] neg_hi:[0,0,1]
	v_pk_fma_f32 v[66:67], v[58:59], v[50:51], v[66:67] neg_lo:[0,0,1] neg_hi:[0,0,1]
	v_pk_mul_f32 v[48:49], v[60:61], v[48:49]
	v_pk_mul_f32 v[50:51], v[62:63], v[50:51]
	s_nop 0
	v_pk_fma_f32 v[54:55], v[58:59], v[54:55], v[50:51]
	v_pk_fma_f32 v[50:51], v[56:57], v[52:53], v[48:49]
	v_lshl_add_u64 v[52:53], v[160:161], 0, v[180:181]
	v_cvt_pk_bf16_f32 v48, v64, v65
	v_cvt_pk_bf16_f32 v49, v66, v67
	v_cvt_pk_bf16_f32 v50, v50, v51
	v_cvt_pk_bf16_f32 v51, v54, v55
	global_store_dwordx4 v[52:53], v[48:51], off sc1
.LBB0_482:
	s_mov_b64 s[78:79], 0
	v_cvt_pk_bf16_f32 v44, v44, v45
	v_cvt_pk_bf16_f32 v45, v40, v41
	v_cvt_pk_bf16_f32 v46, v46, v47
	v_cvt_pk_bf16_f32 v47, v42, v43
	global_store_dwordx4 v[38:39], v[44:47], off offset:256 sc1
.LBB0_483:
	s_and_b64 vcc, exec, s[78:79]
	s_cbranch_vccz .LBB0_485
	v_mov_b32_e32 v38, v36
	v_mov_b32_e32 v39, v36
	v_pk_mul_f32 v[24:25], v[24:25], v[38:39]
	v_pk_mul_f32 v[20:21], v[20:21], v[38:39]
	v_pk_mul_f32 v[18:19], v[18:19], v[36:37]
	v_pk_mul_f32 v[24:25], v[24:25], v[20:21]
	v_pk_mul_f32 v[20:21], v[22:23], v[18:19]
	v_mov_b64_e32 v[22:23], s[46:47]
	v_mad_i64_i32 v[22:23], s[72:73], v178, s77, v[22:23]
	v_lshl_add_u64 v[22:23], s[70:71], 1, v[22:23]
	s_lshl_b32 s48, s91, 1
	v_lshl_add_u64 v[22:23], v[22:23], 0, s[48:49]
	v_pk_mul_f32 v[32:33], v[32:33], v[38:39]
	v_pk_mul_f32 v[28:29], v[28:29], v[38:39]
	v_pk_mul_f32 v[26:27], v[26:27], v[36:37]
	v_lshl_add_u64 v[22:23], v[22:23], 0, v[0:1]
	v_pk_mul_f32 v[28:29], v[32:33], v[28:29]
	v_pk_mul_f32 v[26:27], v[30:31], v[26:27]
	s_nop 0
	v_cvt_pk_bf16_f32 v18, v26, v27
	v_cvt_pk_bf16_f32 v19, v28, v29
	v_cvt_pk_bf16_f32 v20, v20, v21
	v_cvt_pk_bf16_f32 v21, v24, v25
	global_store_dwordx4 v[22:23], v[18:21], off offset:2560 sc1

; __device__ __forceinline__ float dot4(f32x4 a) { return (a[0] * a[0] + a[1] * a[1]) + (a[2] * a[2] + a[3] * a[3]); }
; __device__ __forceinline__ float fq_sum(float s) { s += __shfl_xor(s, 16); s += __shfl_xor(s, 32); return s; }
; __device__ __forceinline__ u32x4 pack8(f32x4 a, f32x4 b) { u32x4 w; w.x = cvt_pk_bf16(a[0], a[1]); w.y = cvt_pk_bf16(a[2], a[3]); w.z = cvt_pk_bf16(b[0], b[1]); w.w = cvt_pk_bf16(b[2], b[3]); return w; }
;     __device__ __forceinline__ void operator()(const f32x4 (&acc)[2][2][4][2], const Unit& u, int wr, int wc, int fr, int fq) const {
;     ...
;                 for (int bj = 0; bj < 2; ++bj) {
;                     const f32x4 v0 = acc[ai][bj][m][0] * rs, v1 = acc[ai][bj][m][1] * rs;
;                     const int hb = 2 * u.pn + bj;
;                     if (hb < 5) { const float s = fq_sum(dot4(v0) + dot4(v1)); if (fq == 0) zs[(size_t)row * 32 + (hb < 3 ? hb * 4 : 16 + (hb - 3) * 4) + wc] = s; }
;                     if (hb == 5 && wc == 0) {
;                         const float ss = fq_sum(dot4(v0) + dot4(v1)); const float rn = rsqrtf(ss * (1.0f / 32.0f) + EPS);
;                         const f32x4 g1 = *(const f32x4*)(gk + 4 * fq), g2 = *(const f32x4*)(gk + 16 + 4 * fq);
;                         const f32x4 c = *(const f32x4*)(cs + (size_t)row * 16 + 4 * fq), s = *(const f32x4*)(sn + (size_t)row * 16 + 4 * fq);
;                         const f32x4 a = v0 * rn * g1, b = v1 * rn * g2;
;                         *(u32x4*)(kpe + (size_t)row * 32 + 8 * fq) = pack8(a * c - b * s, b * c + a * s);
;                     }
;                     *(u32x4*)(z + (size_t)row * INP + colb + bj * 128) = pack8(v0, v1);
.LBB0_494:
	v_cvt_pk_bf16_f32 v24, v14, v15
	s_waitcnt lgkmcnt(0)
	v_cvt_pk_bf16_f32 v25, v20, v21
	v_mov_b64_e32 v[20:21], s[46:47]
	v_mad_i64_i32 v[20:21], s[42:43], v172, s77, v[20:21]
	v_lshl_add_u64 v[20:21], v[176:177], 1, v[20:21]
	v_cvt_pk_bf16_f32 v26, v6, v7
	v_cvt_pk_bf16_f32 v27, v22, v23
	global_store_dwordx4 v[20:21], v[24:27], off sc1
	s_or_b32 s44, s61, 1
	s_cmp_gt_i32 s44, 4
	v_mov_b32_e32 v24, v18
	v_mov_b32_e32 v25, v18
	v_pk_mul_f32 v[22:23], v[12:13], v[24:25]
	v_pk_mul_f32 v[26:27], v[10:11], v[18:19]
	v_pk_mul_f32 v[24:25], v[4:5], v[24:25]
	v_pk_mul_f32 v[28:29], v[2:3], v[18:19]
	s_cbranch_scc1 .LBB0_498
	v_mul_f32_e32 v32, v27, v27
	v_mul_f32_e32 v33, v23, v23
	v_fmac_f32_e32 v32, v26, v26
	v_fmac_f32_e32 v33, v22, v22
	v_add_f32_e32 v32, v32, v33
	v_mul_f32_e32 v33, v29, v29
	v_mul_f32_e32 v34, v25, v25
	v_fmac_f32_e32 v33, v28, v28
	v_fmac_f32_e32 v34, v24, v24
	v_add_f32_e32 v33, v33, v34
	v_add_f32_e32 v32, v32, v33
	ds_bpermute_b32 v33, v232, v32
	s_waitcnt lgkmcnt(0)
	v_add_f32_e32 v32, v32, v33
	ds_bpermute_b32 v33, v233, v32
	s_and_saveexec_b64 s[42:43], s[38:39]
	s_cbranch_execz .LBB0_497
	s_lshl_b32 s4, s44, 2
	s_add_i32 s5, s4, 4
	s_cmp_lt_i32 s44, 3
	s_cselect_b32 s44, s4, s5
	s_ashr_i32 s45, s44, 31
	v_lshl_add_u64 v[30:31], s[50:51], 0, v[30:31]
	v_lshl_add_u64 v[30:31], s[44:45], 2, v[30:31]
	s_lshl_b32 s48, s90, 2
	s_waitcnt lgkmcnt(0)
	v_add_f32_e32 v32, v32, v33
	v_lshl_add_u64 v[30:31], v[30:31], 0, s[48:49]
	global_store_dword v[30:31], v32, off

; __device__ __forceinline__ float dot4(f32x4 a) { return (a[0] * a[0] + a[1] * a[1]) + (a[2] * a[2] + a[3] * a[3]); }
; __device__ __forceinline__ float fq_sum(float s) { s += __shfl_xor(s, 16); s += __shfl_xor(s, 32); return s; }
; __device__ __forceinline__ u32x4 pack8(f32x4 a, f32x4 b) { u32x4 w; w.x = cvt_pk_bf16(a[0], a[1]); w.y = cvt_pk_bf16(a[2], a[3]); w.z = cvt_pk_bf16(b[0], b[1]); w.w = cvt_pk_bf16(b[2], b[3]); return w; }
;     __device__ __forceinline__ void operator()(const f32x4 (&acc)[2][2][4][2], const Unit& u, int wr, int wc, int fr, int fq) const {
;     ...
;                 if (u.pn >= 5) {
;                     const f32x4 u0 = (acc[ai][0][m][0] * rs) * (acc[ai][1][m][0] * rs), u1 = (acc[ai][0][m][1] * rs) * (acc[ai][1][m][1] * rs);
;                     *(u32x4*)(z + (size_t)row * INP + 1280 + (u.pn - 5) * 128 + wc * 32 + 8 * fq) = pack8(u0, u1);
;                 } else
; #pragma unroll
;                 for (int bj = 0; bj < 2; ++bj) {
;                     const f32x4 v0 = acc[ai][bj][m][0] * rs, v1 = acc[ai][bj][m][1] * rs;
;                     const int hb = 2 * u.pn + bj;
;                     if (hb < 5) { const float s = fq_sum(dot4(v0) + dot4(v1)); if (fq == 0) zs[(size_t)row * 32 + (hb < 3 ? hb * 4 : 16 + (hb - 3) * 4) + wc] = s; }
;                     if (hb == 5 && wc == 0) {
;                         const float ss = fq_sum(dot4(v0) + dot4(v1)); const float rn = rsqrtf(ss * (1.0f / 32.0f) + EPS);
;                         const f32x4 g1 = *(const f32x4*)(gk + 4 * fq), g2 = *(const f32x4*)(gk + 16 + 4 * fq);
;                         const f32x4 c = *(const f32x4*)(cs + (size_t)row * 16 + 4 * fq), s = *(const f32x4*)(sn + (size_t)row * 16 + 4 * fq);
;                         const f32x4 a = v0 * rn * g1, b = v1 * rn * g2;
;                         *(u32x4*)(kpe + (size_t)row * 32 + 8 * fq) = pack8(a * c - b * s, b * c + a * s);
;                     }
;                     *(u32x4*)(z + (size_t)row * INP + colb + bj * 128) = pack8(v0, v1);
.LBB0_500:
.LBB0_501:
	v_mov_b32_e32 v32, v27
	s_waitcnt lgkmcnt(0)
	v_mov_b32_e32 v33, v29
	v_mov_b32_e32 v30, v26
	v_mov_b32_e32 v31, v28
	v_pk_mul_f32 v[32:33], v[32:33], v[32:33]
	v_mov_b32_e32 v34, v23
	v_mov_b32_e32 v35, v25
	v_pk_fma_f32 v[30:31], v[30:31], v[30:31], v[32:33]
	v_mov_b32_e32 v32, v22
	v_mov_b32_e32 v33, v24
	v_pk_mul_f32 v[34:35], v[34:35], v[34:35]
	v_lshl_add_u64 v[38:39], v[156:157], 0, v[174:175]
	v_pk_fma_f32 v[32:33], v[32:33], v[32:33], v[34:35]
	v_lshl_add_u64 v[42:43], v[158:159], 0, v[174:175]
	v_pk_add_f32 v[30:31], v[30:31], v[32:33]
	s_nop 0
	v_add_f32_e32 v30, v30, v31
	ds_bpermute_b32 v31, v232, v30
	s_waitcnt lgkmcnt(0)
	v_add_f32_e32 v30, v30, v31
	ds_bpermute_b32 v31, v233, v30
	s_waitcnt lgkmcnt(0)
	v_add_f32_e32 v30, v30, v31
	v_fmamk_f32 v30, v30, 0x3d000000, v162
	v_cmp_gt_f32_e32 vcc, s31, v30
	v_mul_f32_e32 v31, 0x4b800000, v30
	s_nop 0
	v_cndmask_b32_e32 v30, v30, v31, vcc
	v_rsq_f32_e32 v30, v30
	s_nop 0
	v_mul_f32_e32 v31, 0x45800000, v30
	v_cndmask_b32_e32 v46, v30, v31, vcc
	global_load_dwordx4 v[30:33], v[166:167], off
	global_load_dwordx4 v[34:37], v[166:167], off offset:64
	v_pk_mul_f32 v[48:49], v[22:23], v[46:47] op_sel_hi:[1,0]
	global_load_dwordx4 v[38:41], v[38:39], off
	v_pk_mul_f32 v[50:51], v[26:27], v[46:47] op_sel_hi:[1,0]
	global_load_dwordx4 v[42:45], v[42:43], off
	s_waitcnt vmcnt(3)
	v_pk_mul_f32 v[32:33], v[32:33], v[48:49]
	v_pk_mul_f32 v[48:49], v[28:29], v[46:47] op_sel_hi:[1,0]
	v_pk_mul_f32 v[46:47], v[24:25], v[46:47] op_sel_hi:[1,0]
	s_waitcnt vmcnt(2)
	v_pk_mul_f32 v[34:35], v[34:35], v[48:49]
	v_pk_mul_f32 v[36:37], v[36:37], v[46:47]
	v_pk_mul_f32 v[30:31], v[30:31], v[50:51]
	s_waitcnt vmcnt(0)
	v_pk_mul_f32 v[46:47], v[42:43], v[34:35]
	v_pk_mul_f32 v[48:49], v[44:45], v[36:37]
	v_pk_fma_f32 v[46:47], v[38:39], v[30:31], v[46:47] neg_lo:[0,0,1] neg_hi:[0,0,1]
	v_pk_fma_f32 v[48:49], v[40:41], v[32:33], v[48:49] neg_lo:[0,0,1] neg_hi:[0,0,1]
	v_pk_mul_f32 v[30:31], v[42:43], v[30:31]
	v_pk_mul_f32 v[32:33], v[44:45], v[32:33]
	s_nop 0
	v_pk_fma_f32 v[36:37], v[40:41], v[36:37], v[32:33]
	v_pk_fma_f32 v[32:33], v[38:39], v[34:35], v[30:31]
	v_lshl_add_u64 v[34:35], v[160:161], 0, v[174:175]
	v_cvt_pk_bf16_f32 v30, v46, v47
	v_cvt_pk_bf16_f32 v31, v48, v49
	v_cvt_pk_bf16_f32 v32, v32, v33
	v_cvt_pk_bf16_f32 v33, v36, v37
	global_store_dwordx4 v[34:35], v[30:33], off sc1
.LBB0_502:
	v_cvt_pk_bf16_f32 v26, v26, v27
	v_cvt_pk_bf16_f32 v27, v22, v23
	v_cvt_pk_bf16_f32 v28, v28, v29
	v_cvt_pk_bf16_f32 v29, v24, v25
	global_store_dwordx4 v[20:21], v[26:29], off offset:256 sc1
	s_branch .LBB0_487
.LBB0_503:
	v_mov_b32_e32 v20, v18
	v_mov_b32_e32 v21, v18
	v_pk_mul_f32 v[8:9], v[8:9], v[20:21]
	v_pk_mul_f32 v[4:5], v[4:5], v[20:21]
	v_pk_mul_f32 v[2:3], v[2:3], v[18:19]
	v_pk_mul_f32 v[8:9], v[8:9], v[4:5]
	v_pk_mul_f32 v[4:5], v[6:7], v[2:3]
	v_mov_b64_e32 v[6:7], s[46:47]
	v_mad_i64_i32 v[6:7], s[42:43], v172, s77, v[6:7]
	v_lshl_add_u64 v[6:7], s[70:71], 1, v[6:7]
	s_lshl_b32 s48, s91, 1
	v_lshl_add_u64 v[6:7], v[6:7], 0, s[48:49]
	v_pk_mul_f32 v[16:17], v[16:17], v[20:21]
	v_pk_mul_f32 v[12:13], v[12:13], v[20:21]
	v_pk_mul_f32 v[10:11], v[10:11], v[18:19]
	v_lshl_add_u64 v[6:7], v[6:7], 0, v[0:1]
	v_pk_mul_f32 v[12:13], v[16:17], v[12:13]
	v_pk_mul_f32 v[10:11], v[14:15], v[10:11]
	s_nop 0
	v_cvt_pk_bf16_f32 v2, v10, v11
	v_cvt_pk_bf16_f32 v3, v12, v13
	v_cvt_pk_bf16_f32 v4, v4, v5
	v_cvt_pk_bf16_f32 v5, v8, v9
	global_store_dwordx4 v[6:7], v[2:5], off offset:2560 sc1
	s_andn2_b64 vcc, exec, s[40:41]
	s_mov_b64 s[40:41], -1
	s_cbranch_vccnz .LBB0_350
